# RG-LRU sample scan: all 13 loads of the 4 steps issued up front under one wait instead of 8 serialized round trips
# speedup vs baseline: 1.0257x; 1.0058x over previous
; __device__ __forceinline__ float bf2f(bf16_t h) { return __uint_as_float((unsigned)h << 16); }
; __device__ __forceinline__ bf16_t f2bf(float f) { return (bf16_t)(cvt_pk_bf16(f, 0.f) & 0xffffu); }
; __device__ __forceinline__ float gelu_tanh(float x) { const float u = 0.7978845608f * (x + 0.044715f * x * x * x); return 0.5f * x * (1.0f + tanh_f(u)); }
; __device__ __forceinline__ void scan_lru(PP P, int l, LAS unsigned char* lds, const Ids I) {
;     ...
;     for (int g = BID * 512 + tid; g < 128 * 512; g += NB * 512) {
;         const int sb = g >> 9, ch = g & 511; float h = P->in[I_SH][(unsigned)(l * 128 + sb) * 512u + ch];
; #pragma unroll
;         for (unsigned s = 0; s < 4; ++s) { const unsigned row = (unsigned)MTP + sb * 4 + s, o = row * 512u + ch; const float la = bf2f(LA[o]), gx = bf2f(GX[o]); const float a = __expf(la), bb = sqrtf(fmaxf(1.f - a * a, 0.f)) * gx;
;             h = a * h + bb; const float gb = bf2f(PR[row * (unsigned)INW + 512u + ch]); ymix[row * 1024u + ch] = f2bf(h * gelu_tanh(gb)); }
;         out[O_SH + (unsigned)(l * 128 + sb) * 512u + ch] = h;
;     }
.LBB0_58:
	s_load_dwordx2 s[4:5], s[88:89], 0x28
	v_and_b32_e32 v0, 0xfffffe00, v2
	v_and_b32_e32 v3, 0x1ff, v2
	v_add_u32_e32 v0, s0, v0
	v_or_b32_e32 v144, v0, v3
	s_waitcnt lgkmcnt(0)
	v_lshl_add_u64 v[4:5], v[144:145], 2, s[4:5]
	v_ashrrev_i32_e32 v1, 7, v2
	global_load_dword v20, v[4:5], off
	v_and_b32_e32 v4, -4, v1
	v_add_u32_e32 v10, 0x4000, v4
	v_lshl_or_b32 v144, v10, 9, v3
	v_lshlrev_b64 v[6:7], 1, v[144:145]
	v_lshl_add_u64 v[8:9], s[96:97], 0, v[6:7]
	v_lshl_add_u64 v[6:7], s[10:11], 0, v[6:7]
	global_load_ushort v21, v[8:9], off
	global_load_ushort v22, v[6:7], off
	global_load_ushort v24, v[8:9], off offset:1024
	global_load_ushort v25, v[6:7], off offset:1024
	global_load_ushort v27, v[8:9], off offset:2048
	global_load_ushort v28, v[6:7], off offset:2048
	global_load_ushort v30, v[8:9], off offset:3072
	global_load_ushort v31, v[6:7], off offset:3072
	v_mul_lo_u32 v1, v10, s90
	v_or_b32_e32 v1, v3, v1
	v_or_b32_e32 v144, 0x200, v1
	v_lshl_add_u64 v[12:13], v[144:145], 1, s[60:61]
	global_load_ushort v23, v[12:13], off
	v_add_u32_e32 v144, 0xd00, v1
	v_lshl_add_u64 v[12:13], v[144:145], 1, s[60:61]
	global_load_ushort v26, v[12:13], off
	v_add_u32_e32 v144, 0x1800, v1
	v_lshl_add_u64 v[12:13], v[144:145], 1, s[60:61]
	global_load_ushort v29, v[12:13], off
	v_add_u32_e32 v144, 0x2300, v1
	v_lshl_add_u64 v[12:13], v[144:145], 1, s[60:61]
	global_load_ushort v32, v[12:13], off
	v_add_u32_e32 v2, s92, v2
	s_mov_b32 s1, 0xffff
	s_waitcnt vmcnt(0)
	v_lshlrev_b32_e32 v8, 16, v21
	v_mul_f32_e32 v7, 0x3fb8aa3b, v8
	v_exp_f32_e32 v7, v7
	v_lshlrev_b32_e32 v6, 16, v22
	v_fma_f32 v8, -v7, v7, 1.0
	v_max_f32_e32 v8, 0, v8
	v_cmp_gt_f32_e32 vcc, s3, v8
	v_mul_f32_e32 v9, 0x4f800000, v8
	s_nop 0
	v_cndmask_b32_e32 v8, v8, v9, vcc
	v_sqrt_f32_e32 v9, v8
	s_nop 0
	v_add_u32_e32 v11, -1, v9
	v_fma_f32 v12, -v11, v9, v8
	v_cmp_ge_f32_e64 s[4:5], 0, v12
	v_add_u32_e32 v12, 1, v9
	s_nop 0
	v_cndmask_b32_e64 v11, v9, v11, s[4:5]
	v_fma_f32 v9, -v12, v9, v8
	v_cmp_lt_f32_e64 s[4:5], 0, v9
	s_nop 1
	v_cndmask_b32_e64 v9, v11, v12, s[4:5]
	v_mul_f32_e32 v11, 0x37800000, v9
	v_cndmask_b32_e32 v9, v9, v11, vcc
	v_cmp_class_f32_e32 vcc, v8, v175
	s_nop 1
	v_cndmask_b32_e32 v8, v9, v8, vcc
	v_mul_f32_e32 v11, v8, v6
	v_fmac_f32_e32 v11, v20, v7
	v_mov_b32_e32 v20, v11
	v_lshlrev_b32_e32 v5, 16, v23
	v_mul_f32_e32 v6, 0x3d372713, v5
	v_mul_f32_e32 v6, v6, v5
	v_fma_f32 v6, v6, v5, v5
	v_mul_f32_e32 v6, 0x3f4c422a, v6
	v_add_f32_e32 v6, v6, v6
	v_mul_f32_e32 v6, 0x3fb8aa3b, v6
	v_exp_f32_e32 v6, v6
	v_mul_f32_e32 v5, 0.5, v5
	v_add_f32_e32 v6, 1.0, v6
	v_rcp_f32_e32 v6, v6
	s_nop 0
	v_fma_f32 v6, v6, -2.0, 1.0
	v_add_f32_e32 v6, 1.0, v6
	v_mul_f32_e32 v5, v5, v6
	v_mul_f32_e32 v5, v20, v5
	v_cvt_pk_bf16_f32 v5, v5, v145
	v_lshl_or_b32 v144, v10, 10, v3
	v_lshl_add_u64 v[6:7], v[144:145], 1, s[78:79]
	global_store_short v[6:7], v5, off
	v_lshlrev_b32_e32 v8, 16, v24
	v_mul_f32_e32 v7, 0x3fb8aa3b, v8
	v_exp_f32_e32 v7, v7
	v_lshlrev_b32_e32 v6, 16, v25
	v_fma_f32 v8, -v7, v7, 1.0
	v_max_f32_e32 v8, 0, v8
	v_cmp_gt_f32_e32 vcc, s3, v8
	v_mul_f32_e32 v9, 0x4f800000, v8
	s_nop 0
	v_cndmask_b32_e32 v8, v8, v9, vcc
	v_sqrt_f32_e32 v9, v8
	s_nop 0
	v_add_u32_e32 v11, -1, v9
	v_fma_f32 v12, -v11, v9, v8
	v_cmp_ge_f32_e64 s[4:5], 0, v12
	v_add_u32_e32 v12, 1, v9
	s_nop 0
	v_cndmask_b32_e64 v11, v9, v11, s[4:5]
	v_fma_f32 v9, -v12, v9, v8
	v_cmp_lt_f32_e64 s[4:5], 0, v9
	s_nop 1
	v_cndmask_b32_e64 v9, v11, v12, s[4:5]
	v_mul_f32_e32 v11, 0x37800000, v9
	v_cndmask_b32_e32 v9, v9, v11, vcc
	v_cmp_class_f32_e32 vcc, v8, v175
	s_nop 1
	v_cndmask_b32_e32 v8, v9, v8, vcc
	v_mul_f32_e32 v11, v8, v6
	v_fmac_f32_e32 v11, v20, v7
	v_mov_b32_e32 v20, v11
	v_lshlrev_b32_e32 v5, 16, v26
	v_mul_f32_e32 v6, 0x3d372713, v5
	v_mul_f32_e32 v6, v6, v5
	v_fma_f32 v6, v6, v5, v5
	v_mul_f32_e32 v6, 0x3f4c422a, v6
	v_add_f32_e32 v6, v6, v6
	v_mul_f32_e32 v6, 0x3fb8aa3b, v6
	v_exp_f32_e32 v6, v6
	v_mul_f32_e32 v5, 0.5, v5
	v_add_f32_e32 v6, 1.0, v6
	v_rcp_f32_e32 v6, v6
	s_nop 0
	v_fma_f32 v6, v6, -2.0, 1.0
	v_add_f32_e32 v6, 1.0, v6
	v_mul_f32_e32 v5, v5, v6
	v_mul_f32_e32 v5, v20, v5
	v_cvt_pk_bf16_f32 v5, v5, v145
	v_add_u32_e32 v14, 1, v10
	v_lshl_or_b32 v144, v14, 10, v3
	v_lshl_add_u64 v[6:7], v[144:145], 1, s[78:79]
	global_store_short v[6:7], v5, off
	v_lshlrev_b32_e32 v8, 16, v27
	v_mul_f32_e32 v7, 0x3fb8aa3b, v8
	v_exp_f32_e32 v7, v7
	v_lshlrev_b32_e32 v6, 16, v28
	v_fma_f32 v8, -v7, v7, 1.0
	v_max_f32_e32 v8, 0, v8
	v_cmp_gt_f32_e32 vcc, s3, v8
	v_mul_f32_e32 v9, 0x4f800000, v8
	s_nop 0
	v_cndmask_b32_e32 v8, v8, v9, vcc
	v_sqrt_f32_e32 v9, v8
	s_nop 0
	v_add_u32_e32 v11, -1, v9
	v_fma_f32 v12, -v11, v9, v8
	v_cmp_ge_f32_e64 s[4:5], 0, v12
	v_add_u32_e32 v12, 1, v9
	s_nop 0
	v_cndmask_b32_e64 v11, v9, v11, s[4:5]
	v_fma_f32 v9, -v12, v9, v8
	v_cmp_lt_f32_e64 s[4:5], 0, v9
	s_nop 1
	v_cndmask_b32_e64 v9, v11, v12, s[4:5]
	v_mul_f32_e32 v11, 0x37800000, v9
	v_cndmask_b32_e32 v9, v9, v11, vcc
	v_cmp_class_f32_e32 vcc, v8, v175
	s_nop 1
	v_cndmask_b32_e32 v8, v9, v8, vcc
	v_mul_f32_e32 v11, v8, v6
	v_fmac_f32_e32 v11, v20, v7
	v_mov_b32_e32 v20, v11
	v_lshlrev_b32_e32 v5, 16, v29
	v_mul_f32_e32 v6, 0x3d372713, v5
	v_mul_f32_e32 v6, v6, v5
	v_fma_f32 v6, v6, v5, v5
	v_mul_f32_e32 v6, 0x3f4c422a, v6
	v_add_f32_e32 v6, v6, v6
	v_mul_f32_e32 v6, 0x3fb8aa3b, v6
	v_exp_f32_e32 v6, v6
	v_mul_f32_e32 v5, 0.5, v5
	v_add_f32_e32 v6, 1.0, v6
	v_rcp_f32_e32 v6, v6
	s_nop 0
	v_fma_f32 v6, v6, -2.0, 1.0
	v_add_f32_e32 v6, 1.0, v6
	v_mul_f32_e32 v5, v5, v6
	v_mul_f32_e32 v5, v20, v5
	v_cvt_pk_bf16_f32 v5, v5, v145
	v_add_u32_e32 v14, 2, v10
	v_lshl_or_b32 v144, v14, 10, v3
; __device__ __forceinline__ int make_tid(int wv) { int lane_v; asm volatile("v_mbcnt_lo_u32_b32 %0, -1, 0\n\tv_mbcnt_hi_u32_b32 %0, -1, %0" : "=v"(lane_v)); return wv * 64 + lane_v; }
; __device__ __forceinline__ float bf2f(bf16_t h) { return __uint_as_float((unsigned)h << 16); }
; __device__ __forceinline__ bf16_t f2bf(float f) { return (bf16_t)(cvt_pk_bf16(f, 0.f) & 0xffffu); }
; __device__ __forceinline__ void scan_lru(PP P, int l, LAS unsigned char* lds, const Ids I) {
;     ...
;         for (unsigned s = 0; s < 4; ++s) { const unsigned row = (unsigned)MTP + sb * 4 + s, o = row * 512u + ch; const float la = bf2f(LA[o]), gx = bf2f(GX[o]); const float a = __expf(la), bb = sqrtf(fmaxf(1.f - a * a, 0.f)) * gx;
;             h = a * h + bb; const float gb = bf2f(PR[row * (unsigned)INW + 512u + ch]); ymix[row * 1024u + ch] = f2bf(h * gelu_tanh(gb)); }
;         out[O_SH + (unsigned)(l * 128 + sb) * 512u + ch] = h;
; __device__ __forceinline__ void scan_wkv_sample(PP P, int l, const Ids I) {
;     const int tid = make_tid(I.wv), wave = __builtin_amdgcn_readfirstlane(tid >> 6), lane = tid & 63, rowl = lane >> 4, kseg = lane & 15; unsigned char* ws = P->ws;
;     const bf16_t* arr = (const bf16_t*)(ws + WS_R2); const unsigned AS = (unsigned)MT * 512u; bf16_t* ymix = (bf16_t*)(ws + WS_HB);
;     const float* sin_ = P->in[I_SWKV]; float* out = P->out;
;     const int gw = BID * 8 + wave, nw = NB * 8;
;     for (int q = gw; q < 128 * 8 * 16; q += nw) {
;         const int pair = q >> 4, rgp = q & 15, sb = pair >> 3, h = pair & 7, vrow = rgp * 4 + rowl;
;         const unsigned so = ((unsigned)((l * 128 + sb) * 8 + h) * 64u + vrow) * 64u + kseg * 4;
;         f32x4 S = *(const f32x4*)(sin_ + so);
;         f32x4 r_[4], w_[4], k_[4], a_[4], b_[4]; float v_[4];
; #pragma unroll
;         for (int s = 0; s < 4; ++s) { const unsigned row = (unsigned)MTP + sb * 4 + s, o = row * 512u + h * 64 + kseg * 4;
;             r_[s] = unpack4(*(const u32x2*)(arr + A_R * AS + o)); w_[s] = unpack4(*(const u32x2*)(arr + A_EW * AS + o)); k_[s] = unpack4(*(const u32x2*)(arr + A_KF * AS + o));
;             a_[s] = unpack4(*(const u32x2*)(arr + A_KK * AS + o)); b_[s] = unpack4(*(const u32x2*)(arr + A_BB * AS + o)); v_[s] = bf2f(arr[A_V * AS + row * 512u + h * 64 + vrow]); }
	v_lshl_add_u64 v[6:7], v[144:145], 1, s[78:79]
	global_store_short v[6:7], v5, off
	v_lshlrev_b32_e32 v8, 16, v30
	v_mul_f32_e32 v7, 0x3fb8aa3b, v8
	v_exp_f32_e32 v7, v7
	v_lshlrev_b32_e32 v6, 16, v31
	v_fma_f32 v8, -v7, v7, 1.0
	v_max_f32_e32 v8, 0, v8
	v_cmp_gt_f32_e32 vcc, s3, v8
	v_mul_f32_e32 v9, 0x4f800000, v8
	s_nop 0
	v_cndmask_b32_e32 v8, v8, v9, vcc
	v_sqrt_f32_e32 v9, v8
	s_nop 0
	v_add_u32_e32 v11, -1, v9
	v_fma_f32 v12, -v11, v9, v8
	v_cmp_ge_f32_e64 s[4:5], 0, v12
	v_add_u32_e32 v12, 1, v9
	s_nop 0
	v_cndmask_b32_e64 v11, v9, v11, s[4:5]
	v_fma_f32 v9, -v12, v9, v8
	v_cmp_lt_f32_e64 s[4:5], 0, v9
	s_nop 1
	v_cndmask_b32_e64 v9, v11, v12, s[4:5]
	v_mul_f32_e32 v11, 0x37800000, v9
	v_cndmask_b32_e32 v9, v9, v11, vcc
	v_cmp_class_f32_e32 vcc, v8, v175
	s_nop 1
	v_cndmask_b32_e32 v8, v9, v8, vcc
	v_mul_f32_e32 v11, v8, v6
	v_fmac_f32_e32 v11, v20, v7
	v_mov_b32_e32 v20, v11
	v_lshlrev_b32_e32 v5, 16, v32
	v_mul_f32_e32 v6, 0x3d372713, v5
	v_mul_f32_e32 v6, v6, v5
	v_fma_f32 v6, v6, v5, v5
	v_mul_f32_e32 v6, 0x3f4c422a, v6
	v_add_f32_e32 v6, v6, v6
	v_mul_f32_e32 v6, 0x3fb8aa3b, v6
	v_exp_f32_e32 v6, v6
	v_mul_f32_e32 v5, 0.5, v5
	v_add_f32_e32 v6, 1.0, v6
	v_rcp_f32_e32 v6, v6
	s_nop 0
	v_fma_f32 v6, v6, -2.0, 1.0
	v_add_f32_e32 v6, 1.0, v6
	v_mul_f32_e32 v5, v5, v6
	v_mul_f32_e32 v5, v20, v5
	v_cvt_pk_bf16_f32 v5, v5, v145
	v_add_u32_e32 v14, 3, v10
	v_lshl_or_b32 v144, v14, 10, v3
	v_lshl_add_u64 v[6:7], v[144:145], 1, s[78:79]
	global_store_short v[6:7], v5, off
	v_mov_b32_e32 v1, v145
	v_lshl_add_u64 v[0:1], v[0:1], 2, s[12:13]
	v_lshlrev_b32_e32 v144, 2, v3
	v_lshl_add_u64 v[0:1], v[0:1], 0, v[144:145]
	v_add_co_u32_e32 v0, vcc, 0x45bc000, v0
	s_nop 1
	v_addc_co_u32_e32 v1, vcc, 0, v1, vcc
	v_cmp_lt_i32_e32 vcc, s1, v2
	s_or_b64 s[8:9], vcc, s[8:9]
	global_store_dword v[0:1], v20, off
	s_andn2_b64 exec, exec, s[8:9]
	s_cbranch_execnz .LBB0_58
.LBB0_59:
	v_writelane_b32 v254, s36, 50
	s_nop 1
	v_writelane_b32 v254, s37, 51
	v_writelane_b32 v254, s18, 48
	v_writelane_b32 v254, s25, 49
	v_writelane_b32 v254, s47, 54
	s_or_b64 exec, exec, s[6:7]
	v_readlane_b32 s16, v254, 34
	v_writelane_b32 v254, s85, 61
	v_mbcnt_lo_u32_b32 v0, -1, 0
	v_mbcnt_hi_u32_b32 v0, -1, v0
	v_writelane_b32 v254, s67, 62
	v_add_u32_e32 v1, s62, v0
	s_nop 0
	v_readfirstlane_b32 s0, v1
	s_ashr_i32 s1, s0, 6
	v_readlane_b32 s0, v254, 29
	s_add_i32 s0, s1, s0
	s_cmpk_lt_i32 s0, 0x4000
	s_cbranch_scc0 .LBB0_754
	s_waitcnt lgkmcnt(0)
	s_add_u32 s4, s12, 0x47fc000
	s_addc_u32 s5, s13, 0
	s_load_dwordx2 s[6:7], s[88:89], 0x38
	v_bfe_u32 v34, v0, 4, 2
	v_and_b32_e32 v33, 15, v0
	v_lshlrev_b32_e32 v35, 2, v33
	s_lshr_b32 s8, s0, 4
	s_bfe_u32 s9, s0, 0x30001
	s_and_b32 s1, s0, 1
	s_lshl_b32 s1, s1, 5
	s_lshl_b32 s3, s8, 2
	s_add_i32 s13, s3, 0x4000
	s_lshl_b32 s12, s9, 6
	v_readlane_b32 s14, v254, 35
	v_readlane_b32 s15, v254, 36
	v_readlane_b32 s18, v254, 37
	v_readlane_b32 s19, v254, 38
	v_mov_b32_e32 v9, 0
	s_lshl_b32 s3, s13, 9
	v_or_b32_e32 v8, s12, v35
	v_or_b32_e32 v8, s3, v8
	v_lshl_add_u64 v[10:11], v[8:9], 1, s[14:15]
	global_load_dwordx2 v[108:109], v[10:11], off
	global_load_dwordx2 v[110:111], v[10:11], off offset:1024
	global_load_dwordx2 v[112:113], v[10:11], off offset:2048
	global_load_dwordx2 v[114:115], v[10:11], off offset:3072
	s_nop 0
	v_lshl_add_u64 v[10:11], v[8:9], 1, s[74:75]
	global_load_dwordx2 v[116:117], v[10:11], off
	global_load_dwordx2 v[118:119], v[10:11], off offset:1024
	global_load_dwordx2 v[120:121], v[10:11], off offset:2048
	global_load_dwordx2 v[122:123], v[10:11], off offset:3072
	s_nop 0
	v_lshl_add_u64 v[10:11], v[8:9], 1, s[18:19]
	global_load_dwordx2 v[124:125], v[10:11], off
	global_load_dwordx2 v[126:127], v[10:11], off offset:1024
	global_load_dwordx2 v[128:129], v[10:11], off offset:2048
	global_load_dwordx2 v[130:131], v[10:11], off offset:3072
	s_nop 0
	v_lshl_add_u64 v[10:11], v[8:9], 1, s[52:53]
	global_load_dwordx2 v[132:133], v[10:11], off
	global_load_dwordx2 v[134:135], v[10:11], off offset:1024
	global_load_dwordx2 v[136:137], v[10:11], off offset:2048
	global_load_dwordx2 v[138:139], v[10:11], off offset:3072
	s_nop 0
	v_lshl_add_u64 v[10:11], v[8:9], 1, s[70:71]
	global_load_dwordx2 v[140:141], v[10:11], off
	global_load_dwordx2 v[142:143], v[10:11], off offset:1024
	global_load_dwordx2 v[246:247], v[10:11], off offset:2048
	global_load_dwordx2 v[248:249], v[10:11], off offset:3072
	s_nop 0
	v_add_u32_e32 v49, s1, v34
	s_lshl_b32 s3, s8, 3
	s_add_i32 s3, s3, s16
	s_or_b32 s3, s3, s9
	s_lshl_b32 s3, s3, 12
	v_lshlrev_b32_e32 v10, 6, v49
	v_or3_b32 v8, s3, v10, v35
	s_waitcnt lgkmcnt(0)
	v_lshl_add_u64 v[0:1], v[8:9], 2, s[6:7]
	v_lshl_add_u64 v[2:3], v[8:9], 2, s[4:5]
	v_and_b32_e32 v10, 3, v33
	v_add_u32_e32 v8, s13, v10
	v_lshlrev_b32_e32 v8, 9, v8
	v_add3_u32 v8, v8, s12, v49
	v_add_u32_e32 v8, 0x2940000, v8
	v_lshl_add_u64 v[4:5], v[8:9], 1, s[96:97]
	global_load_dwordx4 v[12:15], v[0:1], off
	global_load_ushort v16, v[4:5], off
	global_load_dwordx4 v[54:57], v[0:1], off offset:1024
	global_load_ushort v58, v[4:5], off offset:8
	v_mov_b32_e32 v52, 0x1000
	v_mov_b32_e32 v53, 0
	v_lshl_add_u64 v[50:51], v[0:1], 0, v[52:53]
	v_lshl_add_u64 v[6:7], v[2:3], 0, v[52:53]
	s_and_b32 s3, s0, 7
	s_lshl_b32 s3, s3, 9
	s_add_i32 s3, s3, 0x23000
	v_lshlrev_b32_e32 v17, 7, v33
	v_lshl_add_u32 v17, v34, 2, v17
	v_add_u32_e32 v17, s3, v17
	v_lshrrev_b32_e32 v18, 2, v33
	v_lshlrev_b32_e32 v19, 7, v18
	v_lshl_add_u32 v19, v10, 5, v19
	v_add_u32_e32 v19, s3, v19
	v_add_u32_e32 v8, s13, v18
	v_lshlrev_b32_e32 v8, 10, v8
	s_add_i32 s3, s12, s1
	s_addk_i32 s3, 0x200
	v_lshl_add_u32 v18, v10, 3, v8
	v_add_u32_e32 v8, s3, v18
	v_cmp_eq_u32_e64 s[8:9], 1, v10
	v_cmp_eq_u32_e64 s[12:13], 2, v10
	v_cmp_eq_u32_e64 s[14:15], 3, v10
	v_cmp_gt_u32_e64 s[18:19], 4, v33
	v_lshl_add_u64 v[10:11], v[8:9], 1, s[78:79]
	v_cmp_eq_u32_e64 s[0:1], 0, v34
	s_waitcnt vmcnt(20)
; __device__ __forceinline__ float bf2f(bf16_t h) { return __uint_as_float((unsigned)h << 16); }
; __device__ __forceinline__ f32x4 unpack4(const u32x2 w) { return (f32x4){__uint_as_float(w[0] << 16), __uint_as_float(w[0] & 0xffff0000u), __uint_as_float(w[1] << 16), __uint_as_float(w[1] & 0xffff0000u)}; }
; __device__ __forceinline__ void scan_wkv_sample(PP P, int l, const Ids I) {
;     ...
;         for (int s = 0; s < 4; ++s) { const unsigned row = (unsigned)MTP + sb * 4 + s, o = row * 512u + h * 64 + kseg * 4;
;             r_[s] = unpack4(*(const u32x2*)(arr + A_R * AS + o)); w_[s] = unpack4(*(const u32x2*)(arr + A_EW * AS + o)); k_[s] = unpack4(*(const u32x2*)(arr + A_KF * AS + o));
;             a_[s] = unpack4(*(const u32x2*)(arr + A_KK * AS + o)); b_[s] = unpack4(*(const u32x2*)(arr + A_BB * AS + o)); v_[s] = bf2f(arr[A_V * AS + row * 512u + h * 64 + vrow]); }
; #pragma unroll
;         for (int s = 0; s < 4; ++s) { const unsigned row = (unsigned)MTP + sb * 4 + s;
;             const float p = (S[0] * a_[s][0] + S[1] * a_[s][1]) + (S[2] * a_[s][2] + S[3] * a_[s][3]); const float sa = -row16_allsum(p);
; #pragma unroll
;             for (int j = 0; j < 4; ++j) S[j] = fmaf(S[j], __expf(-w_[s][j]), fmaf(sa, b_[s][j], v_[s] * k_[s][j]));
	v_lshlrev_b32_e32 v152, 16, v108
	v_and_b32_e32 v153, 0xffff0000, v108
	v_lshlrev_b32_e32 v154, 16, v109
	v_and_b32_e32 v155, 0xffff0000, v109
	v_lshlrev_b32_e32 v176, 16, v110
	v_and_b32_e32 v177, 0xffff0000, v110
	v_lshlrev_b32_e32 v178, 16, v111
	v_and_b32_e32 v179, 0xffff0000, v111
	v_lshlrev_b32_e32 v200, 16, v112
	v_and_b32_e32 v201, 0xffff0000, v112
	v_lshlrev_b32_e32 v202, 16, v113
	v_and_b32_e32 v203, 0xffff0000, v113
	v_lshlrev_b32_e32 v220, 16, v114
	v_and_b32_e32 v221, 0xffff0000, v114
	v_lshlrev_b32_e32 v222, 16, v115
	v_and_b32_e32 v223, 0xffff0000, v115
	s_waitcnt vmcnt(16)
	v_lshlrev_b32_e32 v156, 16, v116
	v_and_b32_e32 v157, 0xffff0000, v116
	v_lshlrev_b32_e32 v158, 16, v117
	v_and_b32_e32 v159, 0xffff0000, v117
	v_lshlrev_b32_e32 v180, 16, v118
	v_and_b32_e32 v181, 0xffff0000, v118
	v_lshlrev_b32_e32 v182, 16, v119
	v_and_b32_e32 v183, 0xffff0000, v119
	v_lshlrev_b32_e32 v204, 16, v120
	v_and_b32_e32 v205, 0xffff0000, v120
	v_lshlrev_b32_e32 v206, 16, v121
	v_and_b32_e32 v207, 0xffff0000, v121
	v_lshlrev_b32_e32 v224, 16, v122
	v_and_b32_e32 v225, 0xffff0000, v122
	v_lshlrev_b32_e32 v226, 16, v123
	v_and_b32_e32 v227, 0xffff0000, v123
	v_mul_f32_e32 v156, 0xbfb8aa3b, v156
	v_mul_f32_e32 v157, 0xbfb8aa3b, v157
	v_mul_f32_e32 v158, 0xbfb8aa3b, v158
	v_mul_f32_e32 v159, 0xbfb8aa3b, v159
	v_mul_f32_e32 v180, 0xbfb8aa3b, v180
	v_mul_f32_e32 v181, 0xbfb8aa3b, v181
	v_mul_f32_e32 v182, 0xbfb8aa3b, v182
	v_mul_f32_e32 v183, 0xbfb8aa3b, v183
	v_mul_f32_e32 v204, 0xbfb8aa3b, v204
	v_mul_f32_e32 v205, 0xbfb8aa3b, v205
	v_mul_f32_e32 v206, 0xbfb8aa3b, v206
	v_mul_f32_e32 v207, 0xbfb8aa3b, v207
	v_mul_f32_e32 v224, 0xbfb8aa3b, v224
	v_mul_f32_e32 v225, 0xbfb8aa3b, v225
	v_mul_f32_e32 v226, 0xbfb8aa3b, v226
	v_mul_f32_e32 v227, 0xbfb8aa3b, v227
	v_exp_f32_e32 v156, v156
	v_exp_f32_e32 v157, v157
	v_exp_f32_e32 v158, v158
	v_exp_f32_e32 v159, v159
	v_exp_f32_e32 v180, v180
	v_exp_f32_e32 v181, v181
	v_exp_f32_e32 v182, v182
	v_exp_f32_e32 v183, v183
	v_exp_f32_e32 v204, v204
	v_exp_f32_e32 v205, v205
	v_exp_f32_e32 v206, v206
	v_exp_f32_e32 v207, v207
	v_exp_f32_e32 v224, v224
	v_exp_f32_e32 v225, v225
	v_exp_f32_e32 v226, v226
	v_exp_f32_e32 v227, v227
	s_waitcnt vmcnt(12)
	v_lshlrev_b32_e32 v160, 16, v124
	v_and_b32_e32 v161, 0xffff0000, v124
	v_lshlrev_b32_e32 v162, 16, v125
	v_and_b32_e32 v163, 0xffff0000, v125
	v_lshlrev_b32_e32 v188, 16, v126
	v_and_b32_e32 v189, 0xffff0000, v126
	v_lshlrev_b32_e32 v190, 16, v127
	v_and_b32_e32 v191, 0xffff0000, v127
	v_lshlrev_b32_e32 v208, 16, v128
	v_and_b32_e32 v209, 0xffff0000, v128
	v_lshlrev_b32_e32 v210, 16, v129
	v_and_b32_e32 v211, 0xffff0000, v129
	v_lshlrev_b32_e32 v228, 16, v130
	v_and_b32_e32 v229, 0xffff0000, v130
	v_lshlrev_b32_e32 v230, 16, v131
	v_and_b32_e32 v231, 0xffff0000, v131
	s_waitcnt vmcnt(8)
	v_lshlrev_b32_e32 v164, 16, v132
	v_and_b32_e32 v165, 0xffff0000, v132
	v_lshlrev_b32_e32 v166, 16, v133
	v_and_b32_e32 v167, 0xffff0000, v133
	v_lshlrev_b32_e32 v192, 16, v134
	v_and_b32_e32 v193, 0xffff0000, v134
	v_lshlrev_b32_e32 v194, 16, v135
	v_and_b32_e32 v195, 0xffff0000, v135
	v_lshlrev_b32_e32 v212, 16, v136
	v_and_b32_e32 v213, 0xffff0000, v136
	v_lshlrev_b32_e32 v214, 16, v137
	v_and_b32_e32 v215, 0xffff0000, v137
	v_lshlrev_b32_e32 v232, 16, v138
	v_and_b32_e32 v233, 0xffff0000, v138
	v_lshlrev_b32_e32 v234, 16, v139
	v_and_b32_e32 v235, 0xffff0000, v139
	s_waitcnt vmcnt(4)
	v_lshlrev_b32_e32 v168, 16, v140
	v_and_b32_e32 v169, 0xffff0000, v140
	v_lshlrev_b32_e32 v170, 16, v141
	v_and_b32_e32 v171, 0xffff0000, v141
	v_lshlrev_b32_e32 v196, 16, v142
	v_and_b32_e32 v197, 0xffff0000, v142
	v_lshlrev_b32_e32 v198, 16, v143
	v_and_b32_e32 v199, 0xffff0000, v143
	v_lshlrev_b32_e32 v216, 16, v246
	v_and_b32_e32 v217, 0xffff0000, v246
	v_lshlrev_b32_e32 v218, 16, v247
	v_and_b32_e32 v219, 0xffff0000, v247
	v_lshlrev_b32_e32 v242, 16, v248
	v_and_b32_e32 v243, 0xffff0000, v248
	v_lshlrev_b32_e32 v244, 16, v249
	v_and_b32_e32 v245, 0xffff0000, v249
	s_nop 1
	global_load_dwordx4 v[108:111], v[0:1], off offset:2048
	global_load_ushort v132, v[4:5], off offset:16
	global_load_dwordx4 v[112:115], v[0:1], off offset:3072
	global_load_ushort v133, v[4:5], off offset:24
	global_load_dwordx4 v[116:119], v[50:51], off
	global_load_ushort v134, v[4:5], off offset:32
	global_load_dwordx4 v[120:123], v[50:51], off offset:1024
	global_load_ushort v135, v[4:5], off offset:40
	global_load_dwordx4 v[124:127], v[50:51], off offset:2048
	global_load_ushort v136, v[4:5], off offset:48
	global_load_dwordx4 v[128:131], v[50:51], off offset:3072
	global_load_ushort v137, v[4:5], off offset:56
	s_waitcnt vmcnt(14)
; __device__ __forceinline__ bf16_t f2bf(float f) { return (bf16_t)(cvt_pk_bf16(f, 0.f) & 0xffffu); }
; __device__ __forceinline__ void scan_wkv_sample(PP P, int l, const Ids I) {
;     ...
; #pragma unroll
;         for (int s = 0; s < 4; ++s) { const unsigned row = (unsigned)MTP + sb * 4 + s;
;             const float p = (S[0] * a_[s][0] + S[1] * a_[s][1]) + (S[2] * a_[s][2] + S[3] * a_[s][3]); const float sa = -row16_allsum(p);
; #pragma unroll
;             for (int j = 0; j < 4; ++j) S[j] = fmaf(S[j], __expf(-w_[s][j]), fmaf(sa, b_[s][j], v_[s] * k_[s][j]));
;             const float y = row16_allsum((S[0] * r_[s][0] + S[1] * r_[s][1]) + (S[2] * r_[s][2] + S[3] * r_[s][3]));
;             if (kseg == 0) ymix[row * 1024u + 512u + h * 64 + vrow] = f2bf(y); }
;         *(f32x4*)(out + O_SWKV + so) = S;
	v_lshlrev_b32_e32 v32, 16, v16
	s_nop 1
	v_mov_b32_dpp v24, v32 quad_perm:[0,0,0,0] row_mask:0xf bank_mask:0xf
	v_mov_b32_dpp v26, v32 quad_perm:[1,1,1,1] row_mask:0xf bank_mask:0xf
	v_mov_b32_dpp v28, v32 quad_perm:[2,2,2,2] row_mask:0xf bank_mask:0xf
	v_mov_b32_dpp v30, v32 quad_perm:[3,3,3,3] row_mask:0xf bank_mask:0xf
	v_pk_mul_f32 v[36:37], v[12:13], v[164:165]
	v_pk_mul_f32 v[38:39], v[24:25], v[160:161] op_sel_hi:[0,1]
	v_pk_fma_f32 v[36:37], v[14:15], v[166:167], v[36:37]
	v_pk_mul_f32 v[40:41], v[24:25], v[162:163] op_sel_hi:[0,1]
	v_add_f32_e32 v36, v36, v37
	s_nop 1
	v_add_f32_dpp v36, v36, v36 quad_perm:[1,0,3,2] row_mask:0xf bank_mask:0xf bound_ctrl:1
	s_nop 1
	v_add_f32_dpp v36, v36, v36 quad_perm:[2,3,0,1] row_mask:0xf bank_mask:0xf bound_ctrl:1
	s_nop 1
	v_add_f32_dpp v36, v36, v36 row_half_mirror row_mask:0xf bank_mask:0xf bound_ctrl:1
	s_nop 1
	v_add_f32_dpp v36, v36, v36 row_mirror row_mask:0xf bank_mask:0xf bound_ctrl:1
	v_pk_fma_f32 v[38:39], v[36:37], v[168:169], v[38:39] op_sel_hi:[0,1,1] neg_lo:[1,0,0] neg_hi:[1,0,0]
	v_pk_fma_f32 v[40:41], v[36:37], v[170:171], v[40:41] op_sel_hi:[0,1,1] neg_lo:[1,0,0] neg_hi:[1,0,0]
	v_pk_fma_f32 v[12:13], v[12:13], v[156:157], v[38:39]
	v_pk_fma_f32 v[14:15], v[14:15], v[158:159], v[40:41]
	v_pk_mul_f32 v[36:37], v[12:13], v[192:193]
	v_pk_mul_f32 v[42:43], v[12:13], v[152:153]
	v_pk_mul_f32 v[38:39], v[26:27], v[188:189] op_sel_hi:[0,1]
	v_pk_fma_f32 v[42:43], v[14:15], v[154:155], v[42:43]
	v_pk_fma_f32 v[36:37], v[14:15], v[194:195], v[36:37]
	v_add_f32_e32 v44, v42, v43
	v_pk_mul_f32 v[40:41], v[26:27], v[190:191] op_sel_hi:[0,1]
	v_add_f32_e32 v36, v36, v37
	v_add_f32_dpp v44, v44, v44 quad_perm:[1,0,3,2] row_mask:0xf bank_mask:0xf bound_ctrl:1
	s_nop 0
	v_add_f32_dpp v36, v36, v36 quad_perm:[1,0,3,2] row_mask:0xf bank_mask:0xf bound_ctrl:1
	v_add_f32_dpp v44, v44, v44 quad_perm:[2,3,0,1] row_mask:0xf bank_mask:0xf bound_ctrl:1
	s_nop 0
	v_add_f32_dpp v36, v36, v36 quad_perm:[2,3,0,1] row_mask:0xf bank_mask:0xf bound_ctrl:1
	v_add_f32_dpp v44, v44, v44 row_half_mirror row_mask:0xf bank_mask:0xf bound_ctrl:1
	s_nop 0
	v_add_f32_dpp v36, v36, v36 row_half_mirror row_mask:0xf bank_mask:0xf bound_ctrl:1
	v_add_f32_dpp v44, v44, v44 row_mirror row_mask:0xf bank_mask:0xf bound_ctrl:1
	s_nop 0
	v_add_f32_dpp v36, v36, v36 row_mirror row_mask:0xf bank_mask:0xf bound_ctrl:1
	v_pk_fma_f32 v[38:39], v[36:37], v[196:197], v[38:39] op_sel_hi:[0,1,1] neg_lo:[1,0,0] neg_hi:[1,0,0]
	v_pk_fma_f32 v[40:41], v[36:37], v[198:199], v[40:41] op_sel_hi:[0,1,1] neg_lo:[1,0,0] neg_hi:[1,0,0]
	v_pk_fma_f32 v[12:13], v[12:13], v[180:181], v[38:39]
	v_pk_fma_f32 v[14:15], v[14:15], v[182:183], v[40:41]
	v_pk_mul_f32 v[36:37], v[12:13], v[212:213]
	v_pk_mul_f32 v[42:43], v[12:13], v[176:177]
	v_pk_mul_f32 v[38:39], v[28:29], v[208:209] op_sel_hi:[0,1]
	v_pk_fma_f32 v[42:43], v[14:15], v[178:179], v[42:43]
	v_pk_fma_f32 v[36:37], v[14:15], v[214:215], v[36:37]
	v_add_f32_e32 v45, v42, v43
	v_pk_mul_f32 v[40:41], v[28:29], v[210:211] op_sel_hi:[0,1]
	v_add_f32_e32 v36, v36, v37
	v_add_f32_dpp v45, v45, v45 quad_perm:[1,0,3,2] row_mask:0xf bank_mask:0xf bound_ctrl:1
	s_nop 0
	v_add_f32_dpp v36, v36, v36 quad_perm:[1,0,3,2] row_mask:0xf bank_mask:0xf bound_ctrl:1
	v_add_f32_dpp v45, v45, v45 quad_perm:[2,3,0,1] row_mask:0xf bank_mask:0xf bound_ctrl:1
	s_nop 0
	v_add_f32_dpp v36, v36, v36 quad_perm:[2,3,0,1] row_mask:0xf bank_mask:0xf bound_ctrl:1
	v_add_f32_dpp v45, v45, v45 row_half_mirror row_mask:0xf bank_mask:0xf bound_ctrl:1
	s_nop 0
	v_add_f32_dpp v36, v36, v36 row_half_mirror row_mask:0xf bank_mask:0xf bound_ctrl:1
	v_add_f32_dpp v45, v45, v45 row_mirror row_mask:0xf bank_mask:0xf bound_ctrl:1
	s_nop 0
	v_add_f32_dpp v36, v36, v36 row_mirror row_mask:0xf bank_mask:0xf bound_ctrl:1
	v_pk_fma_f32 v[38:39], v[36:37], v[216:217], v[38:39] op_sel_hi:[0,1,1] neg_lo:[1,0,0] neg_hi:[1,0,0]
	v_pk_fma_f32 v[40:41], v[36:37], v[218:219], v[40:41] op_sel_hi:[0,1,1] neg_lo:[1,0,0] neg_hi:[1,0,0]
	v_pk_fma_f32 v[12:13], v[12:13], v[204:205], v[38:39]
	v_pk_fma_f32 v[14:15], v[14:15], v[206:207], v[40:41]
	v_pk_mul_f32 v[36:37], v[12:13], v[232:233]
	v_pk_mul_f32 v[42:43], v[12:13], v[200:201]
	v_pk_mul_f32 v[38:39], v[30:31], v[228:229] op_sel_hi:[0,1]
	v_pk_fma_f32 v[42:43], v[14:15], v[202:203], v[42:43]
	v_pk_fma_f32 v[36:37], v[14:15], v[234:235], v[36:37]
	v_add_f32_e32 v46, v42, v43
	v_pk_mul_f32 v[40:41], v[30:31], v[230:231] op_sel_hi:[0,1]
	v_add_f32_e32 v36, v36, v37
	v_add_f32_dpp v46, v46, v46 quad_perm:[1,0,3,2] row_mask:0xf bank_mask:0xf bound_ctrl:1
	s_nop 0
	v_add_f32_dpp v36, v36, v36 quad_perm:[1,0,3,2] row_mask:0xf bank_mask:0xf bound_ctrl:1
	v_add_f32_dpp v46, v46, v46 quad_perm:[2,3,0,1] row_mask:0xf bank_mask:0xf bound_ctrl:1
	s_nop 0
	v_add_f32_dpp v36, v36, v36 quad_perm:[2,3,0,1] row_mask:0xf bank_mask:0xf bound_ctrl:1
	v_add_f32_dpp v46, v46, v46 row_half_mirror row_mask:0xf bank_mask:0xf bound_ctrl:1
	s_nop 0
	v_add_f32_dpp v36, v36, v36 row_half_mirror row_mask:0xf bank_mask:0xf bound_ctrl:1
	v_add_f32_dpp v46, v46, v46 row_mirror row_mask:0xf bank_mask:0xf bound_ctrl:1
	s_nop 0
	v_add_f32_dpp v36, v36, v36 row_mirror row_mask:0xf bank_mask:0xf bound_ctrl:1
	v_pk_fma_f32 v[38:39], v[36:37], v[242:243], v[38:39] op_sel_hi:[0,1,1] neg_lo:[1,0,0] neg_hi:[1,0,0]
	v_pk_fma_f32 v[40:41], v[36:37], v[244:245], v[40:41] op_sel_hi:[0,1,1] neg_lo:[1,0,0] neg_hi:[1,0,0]
	v_pk_fma_f32 v[12:13], v[12:13], v[224:225], v[38:39]
	v_pk_fma_f32 v[14:15], v[14:15], v[226:227], v[40:41]
	global_store_dwordx4 v[2:3], v[12:15], off
	v_pk_mul_f32 v[42:43], v[12:13], v[220:221]
	v_pk_fma_f32 v[42:43], v[14:15], v[222:223], v[42:43]
	v_add_f32_e32 v47, v42, v43
	s_nop 1
	v_add_f32_dpp v47, v47, v47 quad_perm:[1,0,3,2] row_mask:0xf bank_mask:0xf bound_ctrl:1
	s_nop 1
	v_add_f32_dpp v47, v47, v47 quad_perm:[2,3,0,1] row_mask:0xf bank_mask:0xf bound_ctrl:1
	s_nop 1
	v_add_f32_dpp v47, v47, v47 row_half_mirror row_mask:0xf bank_mask:0xf bound_ctrl:1
	s_nop 1
	v_add_f32_dpp v47, v47, v47 row_mirror row_mask:0xf bank_mask:0xf bound_ctrl:1
	v_cndmask_b32_e64 v48, v44, v45, s[8:9]
	v_cndmask_b32_e64 v48, v48, v46, s[12:13]
	s_nop 1
	v_cndmask_b32_e64 v48, v48, v47, s[14:15]
	s_and_saveexec_b64 s[6:7], s[18:19]
	ds_write_b32 v17, v48
	s_mov_b64 exec, s[6:7]
	s_waitcnt vmcnt(13)
; __device__ __forceinline__ bf16_t f2bf(float f) { return (bf16_t)(cvt_pk_bf16(f, 0.f) & 0xffffu); }
; __device__ __forceinline__ void scan_wkv_sample(PP P, int l, const Ids I) {
;     ...
; #pragma unroll
;         for (int s = 0; s < 4; ++s) { const unsigned row = (unsigned)MTP + sb * 4 + s;
;             const float p = (S[0] * a_[s][0] + S[1] * a_[s][1]) + (S[2] * a_[s][2] + S[3] * a_[s][3]); const float sa = -row16_allsum(p);
; #pragma unroll
;             for (int j = 0; j < 4; ++j) S[j] = fmaf(S[j], __expf(-w_[s][j]), fmaf(sa, b_[s][j], v_[s] * k_[s][j]));
;             const float y = row16_allsum((S[0] * r_[s][0] + S[1] * r_[s][1]) + (S[2] * r_[s][2] + S[3] * r_[s][3]));
;             if (kseg == 0) ymix[row * 1024u + 512u + h * 64 + vrow] = f2bf(y); }
;         *(f32x4*)(out + O_SWKV + so) = S;
	v_lshlrev_b32_e32 v32, 16, v58
	s_nop 1
	v_mov_b32_dpp v24, v32 quad_perm:[0,0,0,0] row_mask:0xf bank_mask:0xf
	v_mov_b32_dpp v26, v32 quad_perm:[1,1,1,1] row_mask:0xf bank_mask:0xf
	v_mov_b32_dpp v28, v32 quad_perm:[2,2,2,2] row_mask:0xf bank_mask:0xf
	v_mov_b32_dpp v30, v32 quad_perm:[3,3,3,3] row_mask:0xf bank_mask:0xf
	v_pk_mul_f32 v[36:37], v[54:55], v[164:165]
	v_pk_mul_f32 v[38:39], v[24:25], v[160:161] op_sel_hi:[0,1]
	v_pk_fma_f32 v[36:37], v[56:57], v[166:167], v[36:37]
	v_pk_mul_f32 v[40:41], v[24:25], v[162:163] op_sel_hi:[0,1]
	v_add_f32_e32 v36, v36, v37
	s_nop 1
	v_add_f32_dpp v36, v36, v36 quad_perm:[1,0,3,2] row_mask:0xf bank_mask:0xf bound_ctrl:1
	s_nop 1
	v_add_f32_dpp v36, v36, v36 quad_perm:[2,3,0,1] row_mask:0xf bank_mask:0xf bound_ctrl:1
	s_nop 1
	v_add_f32_dpp v36, v36, v36 row_half_mirror row_mask:0xf bank_mask:0xf bound_ctrl:1
	s_nop 1
	v_add_f32_dpp v36, v36, v36 row_mirror row_mask:0xf bank_mask:0xf bound_ctrl:1
	v_pk_fma_f32 v[38:39], v[36:37], v[168:169], v[38:39] op_sel_hi:[0,1,1] neg_lo:[1,0,0] neg_hi:[1,0,0]
	v_pk_fma_f32 v[40:41], v[36:37], v[170:171], v[40:41] op_sel_hi:[0,1,1] neg_lo:[1,0,0] neg_hi:[1,0,0]
	v_pk_fma_f32 v[54:55], v[54:55], v[156:157], v[38:39]
	v_pk_fma_f32 v[56:57], v[56:57], v[158:159], v[40:41]
	v_pk_mul_f32 v[36:37], v[54:55], v[192:193]
	v_pk_mul_f32 v[42:43], v[54:55], v[152:153]
	v_pk_mul_f32 v[38:39], v[26:27], v[188:189] op_sel_hi:[0,1]
	v_pk_fma_f32 v[42:43], v[56:57], v[154:155], v[42:43]
	v_pk_fma_f32 v[36:37], v[56:57], v[194:195], v[36:37]
	v_add_f32_e32 v44, v42, v43
	v_pk_mul_f32 v[40:41], v[26:27], v[190:191] op_sel_hi:[0,1]
	v_add_f32_e32 v36, v36, v37
	v_add_f32_dpp v44, v44, v44 quad_perm:[1,0,3,2] row_mask:0xf bank_mask:0xf bound_ctrl:1
	s_nop 0
	v_add_f32_dpp v36, v36, v36 quad_perm:[1,0,3,2] row_mask:0xf bank_mask:0xf bound_ctrl:1
	v_add_f32_dpp v44, v44, v44 quad_perm:[2,3,0,1] row_mask:0xf bank_mask:0xf bound_ctrl:1
	s_nop 0
	v_add_f32_dpp v36, v36, v36 quad_perm:[2,3,0,1] row_mask:0xf bank_mask:0xf bound_ctrl:1
	v_add_f32_dpp v44, v44, v44 row_half_mirror row_mask:0xf bank_mask:0xf bound_ctrl:1
	s_nop 0
	v_add_f32_dpp v36, v36, v36 row_half_mirror row_mask:0xf bank_mask:0xf bound_ctrl:1
	v_add_f32_dpp v44, v44, v44 row_mirror row_mask:0xf bank_mask:0xf bound_ctrl:1
	s_nop 0
	v_add_f32_dpp v36, v36, v36 row_mirror row_mask:0xf bank_mask:0xf bound_ctrl:1
	v_pk_fma_f32 v[38:39], v[36:37], v[196:197], v[38:39] op_sel_hi:[0,1,1] neg_lo:[1,0,0] neg_hi:[1,0,0]
	v_pk_fma_f32 v[40:41], v[36:37], v[198:199], v[40:41] op_sel_hi:[0,1,1] neg_lo:[1,0,0] neg_hi:[1,0,0]
	v_pk_fma_f32 v[54:55], v[54:55], v[180:181], v[38:39]
	v_pk_fma_f32 v[56:57], v[56:57], v[182:183], v[40:41]
	v_pk_mul_f32 v[36:37], v[54:55], v[212:213]
	v_pk_mul_f32 v[42:43], v[54:55], v[176:177]
	v_pk_mul_f32 v[38:39], v[28:29], v[208:209] op_sel_hi:[0,1]
	v_pk_fma_f32 v[42:43], v[56:57], v[178:179], v[42:43]
	v_pk_fma_f32 v[36:37], v[56:57], v[214:215], v[36:37]
	v_add_f32_e32 v45, v42, v43
	v_pk_mul_f32 v[40:41], v[28:29], v[210:211] op_sel_hi:[0,1]
	v_add_f32_e32 v36, v36, v37
	v_add_f32_dpp v45, v45, v45 quad_perm:[1,0,3,2] row_mask:0xf bank_mask:0xf bound_ctrl:1
	s_nop 0
	v_add_f32_dpp v36, v36, v36 quad_perm:[1,0,3,2] row_mask:0xf bank_mask:0xf bound_ctrl:1
	v_add_f32_dpp v45, v45, v45 quad_perm:[2,3,0,1] row_mask:0xf bank_mask:0xf bound_ctrl:1
	s_nop 0
	v_add_f32_dpp v36, v36, v36 quad_perm:[2,3,0,1] row_mask:0xf bank_mask:0xf bound_ctrl:1
	v_add_f32_dpp v45, v45, v45 row_half_mirror row_mask:0xf bank_mask:0xf bound_ctrl:1
	s_nop 0
	v_add_f32_dpp v36, v36, v36 row_half_mirror row_mask:0xf bank_mask:0xf bound_ctrl:1
	v_add_f32_dpp v45, v45, v45 row_mirror row_mask:0xf bank_mask:0xf bound_ctrl:1
	s_nop 0
	v_add_f32_dpp v36, v36, v36 row_mirror row_mask:0xf bank_mask:0xf bound_ctrl:1
	v_pk_fma_f32 v[38:39], v[36:37], v[216:217], v[38:39] op_sel_hi:[0,1,1] neg_lo:[1,0,0] neg_hi:[1,0,0]
	v_pk_fma_f32 v[40:41], v[36:37], v[218:219], v[40:41] op_sel_hi:[0,1,1] neg_lo:[1,0,0] neg_hi:[1,0,0]
	v_pk_fma_f32 v[54:55], v[54:55], v[204:205], v[38:39]
	v_pk_fma_f32 v[56:57], v[56:57], v[206:207], v[40:41]
	v_pk_mul_f32 v[36:37], v[54:55], v[232:233]
	v_pk_mul_f32 v[42:43], v[54:55], v[200:201]
	v_pk_mul_f32 v[38:39], v[30:31], v[228:229] op_sel_hi:[0,1]
	v_pk_fma_f32 v[42:43], v[56:57], v[202:203], v[42:43]
	v_pk_fma_f32 v[36:37], v[56:57], v[234:235], v[36:37]
	v_add_f32_e32 v46, v42, v43
	v_pk_mul_f32 v[40:41], v[30:31], v[230:231] op_sel_hi:[0,1]
	v_add_f32_e32 v36, v36, v37
	v_add_f32_dpp v46, v46, v46 quad_perm:[1,0,3,2] row_mask:0xf bank_mask:0xf bound_ctrl:1
	s_nop 0
	v_add_f32_dpp v36, v36, v36 quad_perm:[1,0,3,2] row_mask:0xf bank_mask:0xf bound_ctrl:1
	v_add_f32_dpp v46, v46, v46 quad_perm:[2,3,0,1] row_mask:0xf bank_mask:0xf bound_ctrl:1
	s_nop 0
	v_add_f32_dpp v36, v36, v36 quad_perm:[2,3,0,1] row_mask:0xf bank_mask:0xf bound_ctrl:1
	v_add_f32_dpp v46, v46, v46 row_half_mirror row_mask:0xf bank_mask:0xf bound_ctrl:1
	s_nop 0
	v_add_f32_dpp v36, v36, v36 row_half_mirror row_mask:0xf bank_mask:0xf bound_ctrl:1
	v_add_f32_dpp v46, v46, v46 row_mirror row_mask:0xf bank_mask:0xf bound_ctrl:1
	s_nop 0
	v_add_f32_dpp v36, v36, v36 row_mirror row_mask:0xf bank_mask:0xf bound_ctrl:1
	v_pk_fma_f32 v[38:39], v[36:37], v[242:243], v[38:39] op_sel_hi:[0,1,1] neg_lo:[1,0,0] neg_hi:[1,0,0]
	v_pk_fma_f32 v[40:41], v[36:37], v[244:245], v[40:41] op_sel_hi:[0,1,1] neg_lo:[1,0,0] neg_hi:[1,0,0]
	v_pk_fma_f32 v[54:55], v[54:55], v[224:225], v[38:39]
	v_pk_fma_f32 v[56:57], v[56:57], v[226:227], v[40:41]
	global_store_dwordx4 v[2:3], v[54:57], off offset:1024
	v_pk_mul_f32 v[42:43], v[54:55], v[220:221]
	v_pk_fma_f32 v[42:43], v[56:57], v[222:223], v[42:43]
	v_add_f32_e32 v47, v42, v43
	s_nop 1
	v_add_f32_dpp v47, v47, v47 quad_perm:[1,0,3,2] row_mask:0xf bank_mask:0xf bound_ctrl:1
	s_nop 1
	v_add_f32_dpp v47, v47, v47 quad_perm:[2,3,0,1] row_mask:0xf bank_mask:0xf bound_ctrl:1
	s_nop 1
	v_add_f32_dpp v47, v47, v47 row_half_mirror row_mask:0xf bank_mask:0xf bound_ctrl:1
	s_nop 1
	v_add_f32_dpp v47, v47, v47 row_mirror row_mask:0xf bank_mask:0xf bound_ctrl:1
	v_cndmask_b32_e64 v48, v44, v45, s[8:9]
	v_cndmask_b32_e64 v48, v48, v46, s[12:13]
	s_nop 1
	v_cndmask_b32_e64 v48, v48, v47, s[14:15]
	s_and_saveexec_b64 s[6:7], s[18:19]
	ds_write_b32 v17, v48 offset:16
	s_mov_b64 exec, s[6:7]
	s_waitcnt vmcnt(12)
; __device__ __forceinline__ bf16_t f2bf(float f) { return (bf16_t)(cvt_pk_bf16(f, 0.f) & 0xffffu); }
; __device__ __forceinline__ void scan_wkv_sample(PP P, int l, const Ids I) {
;     ...
; #pragma unroll
;         for (int s = 0; s < 4; ++s) { const unsigned row = (unsigned)MTP + sb * 4 + s;
;             const float p = (S[0] * a_[s][0] + S[1] * a_[s][1]) + (S[2] * a_[s][2] + S[3] * a_[s][3]); const float sa = -row16_allsum(p);
; #pragma unroll
;             for (int j = 0; j < 4; ++j) S[j] = fmaf(S[j], __expf(-w_[s][j]), fmaf(sa, b_[s][j], v_[s] * k_[s][j]));
;             const float y = row16_allsum((S[0] * r_[s][0] + S[1] * r_[s][1]) + (S[2] * r_[s][2] + S[3] * r_[s][3]));
;             if (kseg == 0) ymix[row * 1024u + 512u + h * 64 + vrow] = f2bf(y); }
;         *(f32x4*)(out + O_SWKV + so) = S;
	v_lshlrev_b32_e32 v32, 16, v132
	s_nop 1
	v_mov_b32_dpp v24, v32 quad_perm:[0,0,0,0] row_mask:0xf bank_mask:0xf
	v_mov_b32_dpp v26, v32 quad_perm:[1,1,1,1] row_mask:0xf bank_mask:0xf
	v_mov_b32_dpp v28, v32 quad_perm:[2,2,2,2] row_mask:0xf bank_mask:0xf
	v_mov_b32_dpp v30, v32 quad_perm:[3,3,3,3] row_mask:0xf bank_mask:0xf
	v_pk_mul_f32 v[36:37], v[108:109], v[164:165]
	v_pk_mul_f32 v[38:39], v[24:25], v[160:161] op_sel_hi:[0,1]
	v_pk_fma_f32 v[36:37], v[110:111], v[166:167], v[36:37]
	v_pk_mul_f32 v[40:41], v[24:25], v[162:163] op_sel_hi:[0,1]
	v_add_f32_e32 v36, v36, v37
	s_nop 1
	v_add_f32_dpp v36, v36, v36 quad_perm:[1,0,3,2] row_mask:0xf bank_mask:0xf bound_ctrl:1
	s_nop 1
	v_add_f32_dpp v36, v36, v36 quad_perm:[2,3,0,1] row_mask:0xf bank_mask:0xf bound_ctrl:1
	s_nop 1
	v_add_f32_dpp v36, v36, v36 row_half_mirror row_mask:0xf bank_mask:0xf bound_ctrl:1
	s_nop 1
	v_add_f32_dpp v36, v36, v36 row_mirror row_mask:0xf bank_mask:0xf bound_ctrl:1
	v_pk_fma_f32 v[38:39], v[36:37], v[168:169], v[38:39] op_sel_hi:[0,1,1] neg_lo:[1,0,0] neg_hi:[1,0,0]
	v_pk_fma_f32 v[40:41], v[36:37], v[170:171], v[40:41] op_sel_hi:[0,1,1] neg_lo:[1,0,0] neg_hi:[1,0,0]
	v_pk_fma_f32 v[108:109], v[108:109], v[156:157], v[38:39]
	v_pk_fma_f32 v[110:111], v[110:111], v[158:159], v[40:41]
	v_pk_mul_f32 v[36:37], v[108:109], v[192:193]
	v_pk_mul_f32 v[42:43], v[108:109], v[152:153]
	v_pk_mul_f32 v[38:39], v[26:27], v[188:189] op_sel_hi:[0,1]
	v_pk_fma_f32 v[42:43], v[110:111], v[154:155], v[42:43]
	v_pk_fma_f32 v[36:37], v[110:111], v[194:195], v[36:37]
	v_add_f32_e32 v44, v42, v43
	v_pk_mul_f32 v[40:41], v[26:27], v[190:191] op_sel_hi:[0,1]
	v_add_f32_e32 v36, v36, v37
	v_add_f32_dpp v44, v44, v44 quad_perm:[1,0,3,2] row_mask:0xf bank_mask:0xf bound_ctrl:1
	s_nop 0
	v_add_f32_dpp v36, v36, v36 quad_perm:[1,0,3,2] row_mask:0xf bank_mask:0xf bound_ctrl:1
	v_add_f32_dpp v44, v44, v44 quad_perm:[2,3,0,1] row_mask:0xf bank_mask:0xf bound_ctrl:1
	s_nop 0
	v_add_f32_dpp v36, v36, v36 quad_perm:[2,3,0,1] row_mask:0xf bank_mask:0xf bound_ctrl:1
	v_add_f32_dpp v44, v44, v44 row_half_mirror row_mask:0xf bank_mask:0xf bound_ctrl:1
	s_nop 0
	v_add_f32_dpp v36, v36, v36 row_half_mirror row_mask:0xf bank_mask:0xf bound_ctrl:1
	v_add_f32_dpp v44, v44, v44 row_mirror row_mask:0xf bank_mask:0xf bound_ctrl:1
	s_nop 0
	v_add_f32_dpp v36, v36, v36 row_mirror row_mask:0xf bank_mask:0xf bound_ctrl:1
	v_pk_fma_f32 v[38:39], v[36:37], v[196:197], v[38:39] op_sel_hi:[0,1,1] neg_lo:[1,0,0] neg_hi:[1,0,0]
	v_pk_fma_f32 v[40:41], v[36:37], v[198:199], v[40:41] op_sel_hi:[0,1,1] neg_lo:[1,0,0] neg_hi:[1,0,0]
	v_pk_fma_f32 v[108:109], v[108:109], v[180:181], v[38:39]
	v_pk_fma_f32 v[110:111], v[110:111], v[182:183], v[40:41]
	v_pk_mul_f32 v[36:37], v[108:109], v[212:213]
	v_pk_mul_f32 v[42:43], v[108:109], v[176:177]
	v_pk_mul_f32 v[38:39], v[28:29], v[208:209] op_sel_hi:[0,1]
	v_pk_fma_f32 v[42:43], v[110:111], v[178:179], v[42:43]
	v_pk_fma_f32 v[36:37], v[110:111], v[214:215], v[36:37]
	v_add_f32_e32 v45, v42, v43
	v_pk_mul_f32 v[40:41], v[28:29], v[210:211] op_sel_hi:[0,1]
	v_add_f32_e32 v36, v36, v37
	v_add_f32_dpp v45, v45, v45 quad_perm:[1,0,3,2] row_mask:0xf bank_mask:0xf bound_ctrl:1
	s_nop 0
	v_add_f32_dpp v36, v36, v36 quad_perm:[1,0,3,2] row_mask:0xf bank_mask:0xf bound_ctrl:1
	v_add_f32_dpp v45, v45, v45 quad_perm:[2,3,0,1] row_mask:0xf bank_mask:0xf bound_ctrl:1
	s_nop 0
	v_add_f32_dpp v36, v36, v36 quad_perm:[2,3,0,1] row_mask:0xf bank_mask:0xf bound_ctrl:1
	v_add_f32_dpp v45, v45, v45 row_half_mirror row_mask:0xf bank_mask:0xf bound_ctrl:1
	s_nop 0
	v_add_f32_dpp v36, v36, v36 row_half_mirror row_mask:0xf bank_mask:0xf bound_ctrl:1
	v_add_f32_dpp v45, v45, v45 row_mirror row_mask:0xf bank_mask:0xf bound_ctrl:1
	s_nop 0
	v_add_f32_dpp v36, v36, v36 row_mirror row_mask:0xf bank_mask:0xf bound_ctrl:1
	v_pk_fma_f32 v[38:39], v[36:37], v[216:217], v[38:39] op_sel_hi:[0,1,1] neg_lo:[1,0,0] neg_hi:[1,0,0]
	v_pk_fma_f32 v[40:41], v[36:37], v[218:219], v[40:41] op_sel_hi:[0,1,1] neg_lo:[1,0,0] neg_hi:[1,0,0]
	v_pk_fma_f32 v[108:109], v[108:109], v[204:205], v[38:39]
	v_pk_fma_f32 v[110:111], v[110:111], v[206:207], v[40:41]
	v_pk_mul_f32 v[36:37], v[108:109], v[232:233]
	v_pk_mul_f32 v[42:43], v[108:109], v[200:201]
	v_pk_mul_f32 v[38:39], v[30:31], v[228:229] op_sel_hi:[0,1]
	v_pk_fma_f32 v[42:43], v[110:111], v[202:203], v[42:43]
	v_pk_fma_f32 v[36:37], v[110:111], v[234:235], v[36:37]
	v_add_f32_e32 v46, v42, v43
	v_pk_mul_f32 v[40:41], v[30:31], v[230:231] op_sel_hi:[0,1]
	v_add_f32_e32 v36, v36, v37
	v_add_f32_dpp v46, v46, v46 quad_perm:[1,0,3,2] row_mask:0xf bank_mask:0xf bound_ctrl:1
	s_nop 0
	v_add_f32_dpp v36, v36, v36 quad_perm:[1,0,3,2] row_mask:0xf bank_mask:0xf bound_ctrl:1
	v_add_f32_dpp v46, v46, v46 quad_perm:[2,3,0,1] row_mask:0xf bank_mask:0xf bound_ctrl:1
	s_nop 0
	v_add_f32_dpp v36, v36, v36 quad_perm:[2,3,0,1] row_mask:0xf bank_mask:0xf bound_ctrl:1
	v_add_f32_dpp v46, v46, v46 row_half_mirror row_mask:0xf bank_mask:0xf bound_ctrl:1
	s_nop 0
	v_add_f32_dpp v36, v36, v36 row_half_mirror row_mask:0xf bank_mask:0xf bound_ctrl:1
	v_add_f32_dpp v46, v46, v46 row_mirror row_mask:0xf bank_mask:0xf bound_ctrl:1
	s_nop 0
	v_add_f32_dpp v36, v36, v36 row_mirror row_mask:0xf bank_mask:0xf bound_ctrl:1
	v_pk_fma_f32 v[38:39], v[36:37], v[242:243], v[38:39] op_sel_hi:[0,1,1] neg_lo:[1,0,0] neg_hi:[1,0,0]
	v_pk_fma_f32 v[40:41], v[36:37], v[244:245], v[40:41] op_sel_hi:[0,1,1] neg_lo:[1,0,0] neg_hi:[1,0,0]
	v_pk_fma_f32 v[108:109], v[108:109], v[224:225], v[38:39]
	v_pk_fma_f32 v[110:111], v[110:111], v[226:227], v[40:41]
	global_store_dwordx4 v[2:3], v[108:111], off offset:2048
	v_pk_mul_f32 v[42:43], v[108:109], v[220:221]
	v_pk_fma_f32 v[42:43], v[110:111], v[222:223], v[42:43]
	v_add_f32_e32 v47, v42, v43
	s_nop 1
	v_add_f32_dpp v47, v47, v47 quad_perm:[1,0,3,2] row_mask:0xf bank_mask:0xf bound_ctrl:1
	s_nop 1
	v_add_f32_dpp v47, v47, v47 quad_perm:[2,3,0,1] row_mask:0xf bank_mask:0xf bound_ctrl:1
	s_nop 1
	v_add_f32_dpp v47, v47, v47 row_half_mirror row_mask:0xf bank_mask:0xf bound_ctrl:1
	s_nop 1
	v_add_f32_dpp v47, v47, v47 row_mirror row_mask:0xf bank_mask:0xf bound_ctrl:1
	v_cndmask_b32_e64 v48, v44, v45, s[8:9]
	v_cndmask_b32_e64 v48, v48, v46, s[12:13]
	s_nop 1
	v_cndmask_b32_e64 v48, v48, v47, s[14:15]
	s_and_saveexec_b64 s[6:7], s[18:19]
	ds_write_b32 v17, v48 offset:32
	s_mov_b64 exec, s[6:7]
	s_waitcnt vmcnt(11)
; __device__ __forceinline__ bf16_t f2bf(float f) { return (bf16_t)(cvt_pk_bf16(f, 0.f) & 0xffffu); }
; __device__ __forceinline__ void scan_wkv_sample(PP P, int l, const Ids I) {
;     ...
; #pragma unroll
;         for (int s = 0; s < 4; ++s) { const unsigned row = (unsigned)MTP + sb * 4 + s;
;             const float p = (S[0] * a_[s][0] + S[1] * a_[s][1]) + (S[2] * a_[s][2] + S[3] * a_[s][3]); const float sa = -row16_allsum(p);
; #pragma unroll
;             for (int j = 0; j < 4; ++j) S[j] = fmaf(S[j], __expf(-w_[s][j]), fmaf(sa, b_[s][j], v_[s] * k_[s][j]));
;             const float y = row16_allsum((S[0] * r_[s][0] + S[1] * r_[s][1]) + (S[2] * r_[s][2] + S[3] * r_[s][3]));
;             if (kseg == 0) ymix[row * 1024u + 512u + h * 64 + vrow] = f2bf(y); }
;         *(f32x4*)(out + O_SWKV + so) = S;
	v_lshlrev_b32_e32 v32, 16, v133
	s_nop 1
	v_mov_b32_dpp v24, v32 quad_perm:[0,0,0,0] row_mask:0xf bank_mask:0xf
	v_mov_b32_dpp v26, v32 quad_perm:[1,1,1,1] row_mask:0xf bank_mask:0xf
	v_mov_b32_dpp v28, v32 quad_perm:[2,2,2,2] row_mask:0xf bank_mask:0xf
	v_mov_b32_dpp v30, v32 quad_perm:[3,3,3,3] row_mask:0xf bank_mask:0xf
	v_pk_mul_f32 v[36:37], v[112:113], v[164:165]
	v_pk_mul_f32 v[38:39], v[24:25], v[160:161] op_sel_hi:[0,1]
	v_pk_fma_f32 v[36:37], v[114:115], v[166:167], v[36:37]
	v_pk_mul_f32 v[40:41], v[24:25], v[162:163] op_sel_hi:[0,1]
	v_add_f32_e32 v36, v36, v37
	s_nop 1
	v_add_f32_dpp v36, v36, v36 quad_perm:[1,0,3,2] row_mask:0xf bank_mask:0xf bound_ctrl:1
	s_nop 1
	v_add_f32_dpp v36, v36, v36 quad_perm:[2,3,0,1] row_mask:0xf bank_mask:0xf bound_ctrl:1
	s_nop 1
	v_add_f32_dpp v36, v36, v36 row_half_mirror row_mask:0xf bank_mask:0xf bound_ctrl:1
	s_nop 1
	v_add_f32_dpp v36, v36, v36 row_mirror row_mask:0xf bank_mask:0xf bound_ctrl:1
	v_pk_fma_f32 v[38:39], v[36:37], v[168:169], v[38:39] op_sel_hi:[0,1,1] neg_lo:[1,0,0] neg_hi:[1,0,0]
	v_pk_fma_f32 v[40:41], v[36:37], v[170:171], v[40:41] op_sel_hi:[0,1,1] neg_lo:[1,0,0] neg_hi:[1,0,0]
	v_pk_fma_f32 v[112:113], v[112:113], v[156:157], v[38:39]
	v_pk_fma_f32 v[114:115], v[114:115], v[158:159], v[40:41]
	v_pk_mul_f32 v[36:37], v[112:113], v[192:193]
	v_pk_mul_f32 v[42:43], v[112:113], v[152:153]
	v_pk_mul_f32 v[38:39], v[26:27], v[188:189] op_sel_hi:[0,1]
	v_pk_fma_f32 v[42:43], v[114:115], v[154:155], v[42:43]
	v_pk_fma_f32 v[36:37], v[114:115], v[194:195], v[36:37]
	v_add_f32_e32 v44, v42, v43
	v_pk_mul_f32 v[40:41], v[26:27], v[190:191] op_sel_hi:[0,1]
	v_add_f32_e32 v36, v36, v37
	v_add_f32_dpp v44, v44, v44 quad_perm:[1,0,3,2] row_mask:0xf bank_mask:0xf bound_ctrl:1
	s_nop 0
	v_add_f32_dpp v36, v36, v36 quad_perm:[1,0,3,2] row_mask:0xf bank_mask:0xf bound_ctrl:1
	v_add_f32_dpp v44, v44, v44 quad_perm:[2,3,0,1] row_mask:0xf bank_mask:0xf bound_ctrl:1
	s_nop 0
	v_add_f32_dpp v36, v36, v36 quad_perm:[2,3,0,1] row_mask:0xf bank_mask:0xf bound_ctrl:1
	v_add_f32_dpp v44, v44, v44 row_half_mirror row_mask:0xf bank_mask:0xf bound_ctrl:1
	s_nop 0
	v_add_f32_dpp v36, v36, v36 row_half_mirror row_mask:0xf bank_mask:0xf bound_ctrl:1
	v_add_f32_dpp v44, v44, v44 row_mirror row_mask:0xf bank_mask:0xf bound_ctrl:1
	s_nop 0
	v_add_f32_dpp v36, v36, v36 row_mirror row_mask:0xf bank_mask:0xf bound_ctrl:1
	v_pk_fma_f32 v[38:39], v[36:37], v[196:197], v[38:39] op_sel_hi:[0,1,1] neg_lo:[1,0,0] neg_hi:[1,0,0]
	v_pk_fma_f32 v[40:41], v[36:37], v[198:199], v[40:41] op_sel_hi:[0,1,1] neg_lo:[1,0,0] neg_hi:[1,0,0]
	v_pk_fma_f32 v[112:113], v[112:113], v[180:181], v[38:39]
	v_pk_fma_f32 v[114:115], v[114:115], v[182:183], v[40:41]
	v_pk_mul_f32 v[36:37], v[112:113], v[212:213]
	v_pk_mul_f32 v[42:43], v[112:113], v[176:177]
	v_pk_mul_f32 v[38:39], v[28:29], v[208:209] op_sel_hi:[0,1]
	v_pk_fma_f32 v[42:43], v[114:115], v[178:179], v[42:43]
	v_pk_fma_f32 v[36:37], v[114:115], v[214:215], v[36:37]
	v_add_f32_e32 v45, v42, v43
	v_pk_mul_f32 v[40:41], v[28:29], v[210:211] op_sel_hi:[0,1]
	v_add_f32_e32 v36, v36, v37
	v_add_f32_dpp v45, v45, v45 quad_perm:[1,0,3,2] row_mask:0xf bank_mask:0xf bound_ctrl:1
	s_nop 0
	v_add_f32_dpp v36, v36, v36 quad_perm:[1,0,3,2] row_mask:0xf bank_mask:0xf bound_ctrl:1
	v_add_f32_dpp v45, v45, v45 quad_perm:[2,3,0,1] row_mask:0xf bank_mask:0xf bound_ctrl:1
	s_nop 0
	v_add_f32_dpp v36, v36, v36 quad_perm:[2,3,0,1] row_mask:0xf bank_mask:0xf bound_ctrl:1
	v_add_f32_dpp v45, v45, v45 row_half_mirror row_mask:0xf bank_mask:0xf bound_ctrl:1
	s_nop 0
	v_add_f32_dpp v36, v36, v36 row_half_mirror row_mask:0xf bank_mask:0xf bound_ctrl:1
	v_add_f32_dpp v45, v45, v45 row_mirror row_mask:0xf bank_mask:0xf bound_ctrl:1
	s_nop 0
	v_add_f32_dpp v36, v36, v36 row_mirror row_mask:0xf bank_mask:0xf bound_ctrl:1
	v_pk_fma_f32 v[38:39], v[36:37], v[216:217], v[38:39] op_sel_hi:[0,1,1] neg_lo:[1,0,0] neg_hi:[1,0,0]
	v_pk_fma_f32 v[40:41], v[36:37], v[218:219], v[40:41] op_sel_hi:[0,1,1] neg_lo:[1,0,0] neg_hi:[1,0,0]
	v_pk_fma_f32 v[112:113], v[112:113], v[204:205], v[38:39]
	v_pk_fma_f32 v[114:115], v[114:115], v[206:207], v[40:41]
	v_pk_mul_f32 v[36:37], v[112:113], v[232:233]
	v_pk_mul_f32 v[42:43], v[112:113], v[200:201]
	v_pk_mul_f32 v[38:39], v[30:31], v[228:229] op_sel_hi:[0,1]
	v_pk_fma_f32 v[42:43], v[114:115], v[202:203], v[42:43]
	v_pk_fma_f32 v[36:37], v[114:115], v[234:235], v[36:37]
	v_add_f32_e32 v46, v42, v43
	v_pk_mul_f32 v[40:41], v[30:31], v[230:231] op_sel_hi:[0,1]
	v_add_f32_e32 v36, v36, v37
	v_add_f32_dpp v46, v46, v46 quad_perm:[1,0,3,2] row_mask:0xf bank_mask:0xf bound_ctrl:1
	s_nop 0
	v_add_f32_dpp v36, v36, v36 quad_perm:[1,0,3,2] row_mask:0xf bank_mask:0xf bound_ctrl:1
	v_add_f32_dpp v46, v46, v46 quad_perm:[2,3,0,1] row_mask:0xf bank_mask:0xf bound_ctrl:1
	s_nop 0
	v_add_f32_dpp v36, v36, v36 quad_perm:[2,3,0,1] row_mask:0xf bank_mask:0xf bound_ctrl:1
	v_add_f32_dpp v46, v46, v46 row_half_mirror row_mask:0xf bank_mask:0xf bound_ctrl:1
	s_nop 0
	v_add_f32_dpp v36, v36, v36 row_half_mirror row_mask:0xf bank_mask:0xf bound_ctrl:1
	v_add_f32_dpp v46, v46, v46 row_mirror row_mask:0xf bank_mask:0xf bound_ctrl:1
	s_nop 0
	v_add_f32_dpp v36, v36, v36 row_mirror row_mask:0xf bank_mask:0xf bound_ctrl:1
	v_pk_fma_f32 v[38:39], v[36:37], v[242:243], v[38:39] op_sel_hi:[0,1,1] neg_lo:[1,0,0] neg_hi:[1,0,0]
	v_pk_fma_f32 v[40:41], v[36:37], v[244:245], v[40:41] op_sel_hi:[0,1,1] neg_lo:[1,0,0] neg_hi:[1,0,0]
	v_pk_fma_f32 v[112:113], v[112:113], v[224:225], v[38:39]
	v_pk_fma_f32 v[114:115], v[114:115], v[226:227], v[40:41]
	global_store_dwordx4 v[2:3], v[112:115], off offset:3072
	v_pk_mul_f32 v[42:43], v[112:113], v[220:221]
	v_pk_fma_f32 v[42:43], v[114:115], v[222:223], v[42:43]
	v_add_f32_e32 v47, v42, v43
	s_nop 1
	v_add_f32_dpp v47, v47, v47 quad_perm:[1,0,3,2] row_mask:0xf bank_mask:0xf bound_ctrl:1
	s_nop 1
	v_add_f32_dpp v47, v47, v47 quad_perm:[2,3,0,1] row_mask:0xf bank_mask:0xf bound_ctrl:1
	s_nop 1
	v_add_f32_dpp v47, v47, v47 row_half_mirror row_mask:0xf bank_mask:0xf bound_ctrl:1
	s_nop 1
	v_add_f32_dpp v47, v47, v47 row_mirror row_mask:0xf bank_mask:0xf bound_ctrl:1
	v_cndmask_b32_e64 v48, v44, v45, s[8:9]
	v_cndmask_b32_e64 v48, v48, v46, s[12:13]
	s_nop 1
	v_cndmask_b32_e64 v48, v48, v47, s[14:15]
	s_and_saveexec_b64 s[6:7], s[18:19]
	ds_write_b32 v17, v48 offset:48
	s_mov_b64 exec, s[6:7]
	s_waitcnt vmcnt(10)
; __device__ __forceinline__ bf16_t f2bf(float f) { return (bf16_t)(cvt_pk_bf16(f, 0.f) & 0xffffu); }
; __device__ __forceinline__ void scan_wkv_sample(PP P, int l, const Ids I) {
;     ...
; #pragma unroll
;         for (int s = 0; s < 4; ++s) { const unsigned row = (unsigned)MTP + sb * 4 + s;
;             const float p = (S[0] * a_[s][0] + S[1] * a_[s][1]) + (S[2] * a_[s][2] + S[3] * a_[s][3]); const float sa = -row16_allsum(p);
; #pragma unroll
;             for (int j = 0; j < 4; ++j) S[j] = fmaf(S[j], __expf(-w_[s][j]), fmaf(sa, b_[s][j], v_[s] * k_[s][j]));
;             const float y = row16_allsum((S[0] * r_[s][0] + S[1] * r_[s][1]) + (S[2] * r_[s][2] + S[3] * r_[s][3]));
;             if (kseg == 0) ymix[row * 1024u + 512u + h * 64 + vrow] = f2bf(y); }
;         *(f32x4*)(out + O_SWKV + so) = S;
	v_lshlrev_b32_e32 v32, 16, v134
	s_nop 1
	v_mov_b32_dpp v24, v32 quad_perm:[0,0,0,0] row_mask:0xf bank_mask:0xf
	v_mov_b32_dpp v26, v32 quad_perm:[1,1,1,1] row_mask:0xf bank_mask:0xf
	v_mov_b32_dpp v28, v32 quad_perm:[2,2,2,2] row_mask:0xf bank_mask:0xf
	v_mov_b32_dpp v30, v32 quad_perm:[3,3,3,3] row_mask:0xf bank_mask:0xf
	v_pk_mul_f32 v[36:37], v[116:117], v[164:165]
	v_pk_mul_f32 v[38:39], v[24:25], v[160:161] op_sel_hi:[0,1]
	v_pk_fma_f32 v[36:37], v[118:119], v[166:167], v[36:37]
	v_pk_mul_f32 v[40:41], v[24:25], v[162:163] op_sel_hi:[0,1]
	v_add_f32_e32 v36, v36, v37
	s_nop 1
	v_add_f32_dpp v36, v36, v36 quad_perm:[1,0,3,2] row_mask:0xf bank_mask:0xf bound_ctrl:1
	s_nop 1
	v_add_f32_dpp v36, v36, v36 quad_perm:[2,3,0,1] row_mask:0xf bank_mask:0xf bound_ctrl:1
	s_nop 1
	v_add_f32_dpp v36, v36, v36 row_half_mirror row_mask:0xf bank_mask:0xf bound_ctrl:1
	s_nop 1
	v_add_f32_dpp v36, v36, v36 row_mirror row_mask:0xf bank_mask:0xf bound_ctrl:1
	v_pk_fma_f32 v[38:39], v[36:37], v[168:169], v[38:39] op_sel_hi:[0,1,1] neg_lo:[1,0,0] neg_hi:[1,0,0]
	v_pk_fma_f32 v[40:41], v[36:37], v[170:171], v[40:41] op_sel_hi:[0,1,1] neg_lo:[1,0,0] neg_hi:[1,0,0]
	v_pk_fma_f32 v[116:117], v[116:117], v[156:157], v[38:39]
	v_pk_fma_f32 v[118:119], v[118:119], v[158:159], v[40:41]
	v_pk_mul_f32 v[36:37], v[116:117], v[192:193]
	v_pk_mul_f32 v[42:43], v[116:117], v[152:153]
	v_pk_mul_f32 v[38:39], v[26:27], v[188:189] op_sel_hi:[0,1]
	v_pk_fma_f32 v[42:43], v[118:119], v[154:155], v[42:43]
	v_pk_fma_f32 v[36:37], v[118:119], v[194:195], v[36:37]
	v_add_f32_e32 v44, v42, v43
	v_pk_mul_f32 v[40:41], v[26:27], v[190:191] op_sel_hi:[0,1]
	v_add_f32_e32 v36, v36, v37
	v_add_f32_dpp v44, v44, v44 quad_perm:[1,0,3,2] row_mask:0xf bank_mask:0xf bound_ctrl:1
	s_nop 0
	v_add_f32_dpp v36, v36, v36 quad_perm:[1,0,3,2] row_mask:0xf bank_mask:0xf bound_ctrl:1
	v_add_f32_dpp v44, v44, v44 quad_perm:[2,3,0,1] row_mask:0xf bank_mask:0xf bound_ctrl:1
	s_nop 0
	v_add_f32_dpp v36, v36, v36 quad_perm:[2,3,0,1] row_mask:0xf bank_mask:0xf bound_ctrl:1
	v_add_f32_dpp v44, v44, v44 row_half_mirror row_mask:0xf bank_mask:0xf bound_ctrl:1
	s_nop 0
	v_add_f32_dpp v36, v36, v36 row_half_mirror row_mask:0xf bank_mask:0xf bound_ctrl:1
	v_add_f32_dpp v44, v44, v44 row_mirror row_mask:0xf bank_mask:0xf bound_ctrl:1
	s_nop 0
	v_add_f32_dpp v36, v36, v36 row_mirror row_mask:0xf bank_mask:0xf bound_ctrl:1
	v_pk_fma_f32 v[38:39], v[36:37], v[196:197], v[38:39] op_sel_hi:[0,1,1] neg_lo:[1,0,0] neg_hi:[1,0,0]
	v_pk_fma_f32 v[40:41], v[36:37], v[198:199], v[40:41] op_sel_hi:[0,1,1] neg_lo:[1,0,0] neg_hi:[1,0,0]
	v_pk_fma_f32 v[116:117], v[116:117], v[180:181], v[38:39]
	v_pk_fma_f32 v[118:119], v[118:119], v[182:183], v[40:41]
	v_pk_mul_f32 v[36:37], v[116:117], v[212:213]
	v_pk_mul_f32 v[42:43], v[116:117], v[176:177]
	v_pk_mul_f32 v[38:39], v[28:29], v[208:209] op_sel_hi:[0,1]
	v_pk_fma_f32 v[42:43], v[118:119], v[178:179], v[42:43]
	v_pk_fma_f32 v[36:37], v[118:119], v[214:215], v[36:37]
	v_add_f32_e32 v45, v42, v43
	v_pk_mul_f32 v[40:41], v[28:29], v[210:211] op_sel_hi:[0,1]
	v_add_f32_e32 v36, v36, v37
	v_add_f32_dpp v45, v45, v45 quad_perm:[1,0,3,2] row_mask:0xf bank_mask:0xf bound_ctrl:1
	s_nop 0
	v_add_f32_dpp v36, v36, v36 quad_perm:[1,0,3,2] row_mask:0xf bank_mask:0xf bound_ctrl:1
	v_add_f32_dpp v45, v45, v45 quad_perm:[2,3,0,1] row_mask:0xf bank_mask:0xf bound_ctrl:1
	s_nop 0
	v_add_f32_dpp v36, v36, v36 quad_perm:[2,3,0,1] row_mask:0xf bank_mask:0xf bound_ctrl:1
	v_add_f32_dpp v45, v45, v45 row_half_mirror row_mask:0xf bank_mask:0xf bound_ctrl:1
	s_nop 0
	v_add_f32_dpp v36, v36, v36 row_half_mirror row_mask:0xf bank_mask:0xf bound_ctrl:1
	v_add_f32_dpp v45, v45, v45 row_mirror row_mask:0xf bank_mask:0xf bound_ctrl:1
	s_nop 0
	v_add_f32_dpp v36, v36, v36 row_mirror row_mask:0xf bank_mask:0xf bound_ctrl:1
	v_pk_fma_f32 v[38:39], v[36:37], v[216:217], v[38:39] op_sel_hi:[0,1,1] neg_lo:[1,0,0] neg_hi:[1,0,0]
	v_pk_fma_f32 v[40:41], v[36:37], v[218:219], v[40:41] op_sel_hi:[0,1,1] neg_lo:[1,0,0] neg_hi:[1,0,0]
	v_pk_fma_f32 v[116:117], v[116:117], v[204:205], v[38:39]
	v_pk_fma_f32 v[118:119], v[118:119], v[206:207], v[40:41]
	v_pk_mul_f32 v[36:37], v[116:117], v[232:233]
	v_pk_mul_f32 v[42:43], v[116:117], v[200:201]
	v_pk_mul_f32 v[38:39], v[30:31], v[228:229] op_sel_hi:[0,1]
	v_pk_fma_f32 v[42:43], v[118:119], v[202:203], v[42:43]
	v_pk_fma_f32 v[36:37], v[118:119], v[234:235], v[36:37]
	v_add_f32_e32 v46, v42, v43
	v_pk_mul_f32 v[40:41], v[30:31], v[230:231] op_sel_hi:[0,1]
	v_add_f32_e32 v36, v36, v37
	v_add_f32_dpp v46, v46, v46 quad_perm:[1,0,3,2] row_mask:0xf bank_mask:0xf bound_ctrl:1
	s_nop 0
	v_add_f32_dpp v36, v36, v36 quad_perm:[1,0,3,2] row_mask:0xf bank_mask:0xf bound_ctrl:1
	v_add_f32_dpp v46, v46, v46 quad_perm:[2,3,0,1] row_mask:0xf bank_mask:0xf bound_ctrl:1
	s_nop 0
	v_add_f32_dpp v36, v36, v36 quad_perm:[2,3,0,1] row_mask:0xf bank_mask:0xf bound_ctrl:1
	v_add_f32_dpp v46, v46, v46 row_half_mirror row_mask:0xf bank_mask:0xf bound_ctrl:1
	s_nop 0
	v_add_f32_dpp v36, v36, v36 row_half_mirror row_mask:0xf bank_mask:0xf bound_ctrl:1
	v_add_f32_dpp v46, v46, v46 row_mirror row_mask:0xf bank_mask:0xf bound_ctrl:1
	s_nop 0
	v_add_f32_dpp v36, v36, v36 row_mirror row_mask:0xf bank_mask:0xf bound_ctrl:1
	v_pk_fma_f32 v[38:39], v[36:37], v[242:243], v[38:39] op_sel_hi:[0,1,1] neg_lo:[1,0,0] neg_hi:[1,0,0]
	v_pk_fma_f32 v[40:41], v[36:37], v[244:245], v[40:41] op_sel_hi:[0,1,1] neg_lo:[1,0,0] neg_hi:[1,0,0]
	v_pk_fma_f32 v[116:117], v[116:117], v[224:225], v[38:39]
	v_pk_fma_f32 v[118:119], v[118:119], v[226:227], v[40:41]
	global_store_dwordx4 v[6:7], v[116:119], off
	v_pk_mul_f32 v[42:43], v[116:117], v[220:221]
	v_pk_fma_f32 v[42:43], v[118:119], v[222:223], v[42:43]
	v_add_f32_e32 v47, v42, v43
	s_nop 1
	v_add_f32_dpp v47, v47, v47 quad_perm:[1,0,3,2] row_mask:0xf bank_mask:0xf bound_ctrl:1
	s_nop 1
	v_add_f32_dpp v47, v47, v47 quad_perm:[2,3,0,1] row_mask:0xf bank_mask:0xf bound_ctrl:1
	s_nop 1
	v_add_f32_dpp v47, v47, v47 row_half_mirror row_mask:0xf bank_mask:0xf bound_ctrl:1
	s_nop 1
	v_add_f32_dpp v47, v47, v47 row_mirror row_mask:0xf bank_mask:0xf bound_ctrl:1
	v_cndmask_b32_e64 v48, v44, v45, s[8:9]
	v_cndmask_b32_e64 v48, v48, v46, s[12:13]
	s_nop 1
	v_cndmask_b32_e64 v48, v48, v47, s[14:15]
	s_and_saveexec_b64 s[6:7], s[18:19]
	ds_write_b32 v17, v48 offset:64
	s_mov_b64 exec, s[6:7]
	s_waitcnt vmcnt(9)
; __device__ __forceinline__ bf16_t f2bf(float f) { return (bf16_t)(cvt_pk_bf16(f, 0.f) & 0xffffu); }
; __device__ __forceinline__ void scan_wkv_sample(PP P, int l, const Ids I) {
;     ...
; #pragma unroll
;         for (int s = 0; s < 4; ++s) { const unsigned row = (unsigned)MTP + sb * 4 + s;
;             const float p = (S[0] * a_[s][0] + S[1] * a_[s][1]) + (S[2] * a_[s][2] + S[3] * a_[s][3]); const float sa = -row16_allsum(p);
; #pragma unroll
;             for (int j = 0; j < 4; ++j) S[j] = fmaf(S[j], __expf(-w_[s][j]), fmaf(sa, b_[s][j], v_[s] * k_[s][j]));
;             const float y = row16_allsum((S[0] * r_[s][0] + S[1] * r_[s][1]) + (S[2] * r_[s][2] + S[3] * r_[s][3]));
;             if (kseg == 0) ymix[row * 1024u + 512u + h * 64 + vrow] = f2bf(y); }
;         *(f32x4*)(out + O_SWKV + so) = S;
	v_lshlrev_b32_e32 v32, 16, v135
	s_nop 1
	v_mov_b32_dpp v24, v32 quad_perm:[0,0,0,0] row_mask:0xf bank_mask:0xf
	v_mov_b32_dpp v26, v32 quad_perm:[1,1,1,1] row_mask:0xf bank_mask:0xf
	v_mov_b32_dpp v28, v32 quad_perm:[2,2,2,2] row_mask:0xf bank_mask:0xf
	v_mov_b32_dpp v30, v32 quad_perm:[3,3,3,3] row_mask:0xf bank_mask:0xf
	v_pk_mul_f32 v[36:37], v[120:121], v[164:165]
	v_pk_mul_f32 v[38:39], v[24:25], v[160:161] op_sel_hi:[0,1]
	v_pk_fma_f32 v[36:37], v[122:123], v[166:167], v[36:37]
	v_pk_mul_f32 v[40:41], v[24:25], v[162:163] op_sel_hi:[0,1]
	v_add_f32_e32 v36, v36, v37
	s_nop 1
	v_add_f32_dpp v36, v36, v36 quad_perm:[1,0,3,2] row_mask:0xf bank_mask:0xf bound_ctrl:1
	s_nop 1
	v_add_f32_dpp v36, v36, v36 quad_perm:[2,3,0,1] row_mask:0xf bank_mask:0xf bound_ctrl:1
	s_nop 1
	v_add_f32_dpp v36, v36, v36 row_half_mirror row_mask:0xf bank_mask:0xf bound_ctrl:1
	s_nop 1
	v_add_f32_dpp v36, v36, v36 row_mirror row_mask:0xf bank_mask:0xf bound_ctrl:1
	v_pk_fma_f32 v[38:39], v[36:37], v[168:169], v[38:39] op_sel_hi:[0,1,1] neg_lo:[1,0,0] neg_hi:[1,0,0]
	v_pk_fma_f32 v[40:41], v[36:37], v[170:171], v[40:41] op_sel_hi:[0,1,1] neg_lo:[1,0,0] neg_hi:[1,0,0]
	v_pk_fma_f32 v[120:121], v[120:121], v[156:157], v[38:39]
	v_pk_fma_f32 v[122:123], v[122:123], v[158:159], v[40:41]
	v_pk_mul_f32 v[36:37], v[120:121], v[192:193]
	v_pk_mul_f32 v[42:43], v[120:121], v[152:153]
	v_pk_mul_f32 v[38:39], v[26:27], v[188:189] op_sel_hi:[0,1]
	v_pk_fma_f32 v[42:43], v[122:123], v[154:155], v[42:43]
	v_pk_fma_f32 v[36:37], v[122:123], v[194:195], v[36:37]
	v_add_f32_e32 v44, v42, v43
	v_pk_mul_f32 v[40:41], v[26:27], v[190:191] op_sel_hi:[0,1]
	v_add_f32_e32 v36, v36, v37
	v_add_f32_dpp v44, v44, v44 quad_perm:[1,0,3,2] row_mask:0xf bank_mask:0xf bound_ctrl:1
	s_nop 0
	v_add_f32_dpp v36, v36, v36 quad_perm:[1,0,3,2] row_mask:0xf bank_mask:0xf bound_ctrl:1
	v_add_f32_dpp v44, v44, v44 quad_perm:[2,3,0,1] row_mask:0xf bank_mask:0xf bound_ctrl:1
	s_nop 0
	v_add_f32_dpp v36, v36, v36 quad_perm:[2,3,0,1] row_mask:0xf bank_mask:0xf bound_ctrl:1
	v_add_f32_dpp v44, v44, v44 row_half_mirror row_mask:0xf bank_mask:0xf bound_ctrl:1
	s_nop 0
	v_add_f32_dpp v36, v36, v36 row_half_mirror row_mask:0xf bank_mask:0xf bound_ctrl:1
	v_add_f32_dpp v44, v44, v44 row_mirror row_mask:0xf bank_mask:0xf bound_ctrl:1
	s_nop 0
	v_add_f32_dpp v36, v36, v36 row_mirror row_mask:0xf bank_mask:0xf bound_ctrl:1
	v_pk_fma_f32 v[38:39], v[36:37], v[196:197], v[38:39] op_sel_hi:[0,1,1] neg_lo:[1,0,0] neg_hi:[1,0,0]
	v_pk_fma_f32 v[40:41], v[36:37], v[198:199], v[40:41] op_sel_hi:[0,1,1] neg_lo:[1,0,0] neg_hi:[1,0,0]
	v_pk_fma_f32 v[120:121], v[120:121], v[180:181], v[38:39]
	v_pk_fma_f32 v[122:123], v[122:123], v[182:183], v[40:41]
	v_pk_mul_f32 v[36:37], v[120:121], v[212:213]
	v_pk_mul_f32 v[42:43], v[120:121], v[176:177]
	v_pk_mul_f32 v[38:39], v[28:29], v[208:209] op_sel_hi:[0,1]
	v_pk_fma_f32 v[42:43], v[122:123], v[178:179], v[42:43]
	v_pk_fma_f32 v[36:37], v[122:123], v[214:215], v[36:37]
	v_add_f32_e32 v45, v42, v43
	v_pk_mul_f32 v[40:41], v[28:29], v[210:211] op_sel_hi:[0,1]
	v_add_f32_e32 v36, v36, v37
	v_add_f32_dpp v45, v45, v45 quad_perm:[1,0,3,2] row_mask:0xf bank_mask:0xf bound_ctrl:1
	s_nop 0
	v_add_f32_dpp v36, v36, v36 quad_perm:[1,0,3,2] row_mask:0xf bank_mask:0xf bound_ctrl:1
	v_add_f32_dpp v45, v45, v45 quad_perm:[2,3,0,1] row_mask:0xf bank_mask:0xf bound_ctrl:1
	s_nop 0
	v_add_f32_dpp v36, v36, v36 quad_perm:[2,3,0,1] row_mask:0xf bank_mask:0xf bound_ctrl:1
	v_add_f32_dpp v45, v45, v45 row_half_mirror row_mask:0xf bank_mask:0xf bound_ctrl:1
	s_nop 0
	v_add_f32_dpp v36, v36, v36 row_half_mirror row_mask:0xf bank_mask:0xf bound_ctrl:1
	v_add_f32_dpp v45, v45, v45 row_mirror row_mask:0xf bank_mask:0xf bound_ctrl:1
	s_nop 0
	v_add_f32_dpp v36, v36, v36 row_mirror row_mask:0xf bank_mask:0xf bound_ctrl:1
	v_pk_fma_f32 v[38:39], v[36:37], v[216:217], v[38:39] op_sel_hi:[0,1,1] neg_lo:[1,0,0] neg_hi:[1,0,0]
	v_pk_fma_f32 v[40:41], v[36:37], v[218:219], v[40:41] op_sel_hi:[0,1,1] neg_lo:[1,0,0] neg_hi:[1,0,0]
	v_pk_fma_f32 v[120:121], v[120:121], v[204:205], v[38:39]
	v_pk_fma_f32 v[122:123], v[122:123], v[206:207], v[40:41]
	v_pk_mul_f32 v[36:37], v[120:121], v[232:233]
	v_pk_mul_f32 v[42:43], v[120:121], v[200:201]
	v_pk_mul_f32 v[38:39], v[30:31], v[228:229] op_sel_hi:[0,1]
	v_pk_fma_f32 v[42:43], v[122:123], v[202:203], v[42:43]
	v_pk_fma_f32 v[36:37], v[122:123], v[234:235], v[36:37]
	v_add_f32_e32 v46, v42, v43
	v_pk_mul_f32 v[40:41], v[30:31], v[230:231] op_sel_hi:[0,1]
	v_add_f32_e32 v36, v36, v37
	v_add_f32_dpp v46, v46, v46 quad_perm:[1,0,3,2] row_mask:0xf bank_mask:0xf bound_ctrl:1
	s_nop 0
	v_add_f32_dpp v36, v36, v36 quad_perm:[1,0,3,2] row_mask:0xf bank_mask:0xf bound_ctrl:1
	v_add_f32_dpp v46, v46, v46 quad_perm:[2,3,0,1] row_mask:0xf bank_mask:0xf bound_ctrl:1
	s_nop 0
	v_add_f32_dpp v36, v36, v36 quad_perm:[2,3,0,1] row_mask:0xf bank_mask:0xf bound_ctrl:1
	v_add_f32_dpp v46, v46, v46 row_half_mirror row_mask:0xf bank_mask:0xf bound_ctrl:1
	s_nop 0
	v_add_f32_dpp v36, v36, v36 row_half_mirror row_mask:0xf bank_mask:0xf bound_ctrl:1
	v_add_f32_dpp v46, v46, v46 row_mirror row_mask:0xf bank_mask:0xf bound_ctrl:1
	s_nop 0
	v_add_f32_dpp v36, v36, v36 row_mirror row_mask:0xf bank_mask:0xf bound_ctrl:1
	v_pk_fma_f32 v[38:39], v[36:37], v[242:243], v[38:39] op_sel_hi:[0,1,1] neg_lo:[1,0,0] neg_hi:[1,0,0]
	v_pk_fma_f32 v[40:41], v[36:37], v[244:245], v[40:41] op_sel_hi:[0,1,1] neg_lo:[1,0,0] neg_hi:[1,0,0]
	v_pk_fma_f32 v[120:121], v[120:121], v[224:225], v[38:39]
	v_pk_fma_f32 v[122:123], v[122:123], v[226:227], v[40:41]
	global_store_dwordx4 v[6:7], v[120:123], off offset:1024
	v_pk_mul_f32 v[42:43], v[120:121], v[220:221]
	v_pk_fma_f32 v[42:43], v[122:123], v[222:223], v[42:43]
	v_add_f32_e32 v47, v42, v43
	s_nop 1
	v_add_f32_dpp v47, v47, v47 quad_perm:[1,0,3,2] row_mask:0xf bank_mask:0xf bound_ctrl:1
	s_nop 1
	v_add_f32_dpp v47, v47, v47 quad_perm:[2,3,0,1] row_mask:0xf bank_mask:0xf bound_ctrl:1
	s_nop 1
	v_add_f32_dpp v47, v47, v47 row_half_mirror row_mask:0xf bank_mask:0xf bound_ctrl:1
	s_nop 1
	v_add_f32_dpp v47, v47, v47 row_mirror row_mask:0xf bank_mask:0xf bound_ctrl:1
	v_cndmask_b32_e64 v48, v44, v45, s[8:9]
	v_cndmask_b32_e64 v48, v48, v46, s[12:13]
	s_nop 1
	v_cndmask_b32_e64 v48, v48, v47, s[14:15]
	s_and_saveexec_b64 s[6:7], s[18:19]
	ds_write_b32 v17, v48 offset:80
	s_mov_b64 exec, s[6:7]
	s_waitcnt vmcnt(8)
; __device__ __forceinline__ bf16_t f2bf(float f) { return (bf16_t)(cvt_pk_bf16(f, 0.f) & 0xffffu); }
; __device__ __forceinline__ void scan_wkv_sample(PP P, int l, const Ids I) {
;     ...
; #pragma unroll
;         for (int s = 0; s < 4; ++s) { const unsigned row = (unsigned)MTP + sb * 4 + s;
;             const float p = (S[0] * a_[s][0] + S[1] * a_[s][1]) + (S[2] * a_[s][2] + S[3] * a_[s][3]); const float sa = -row16_allsum(p);
; #pragma unroll
;             for (int j = 0; j < 4; ++j) S[j] = fmaf(S[j], __expf(-w_[s][j]), fmaf(sa, b_[s][j], v_[s] * k_[s][j]));
;             const float y = row16_allsum((S[0] * r_[s][0] + S[1] * r_[s][1]) + (S[2] * r_[s][2] + S[3] * r_[s][3]));
;             if (kseg == 0) ymix[row * 1024u + 512u + h * 64 + vrow] = f2bf(y); }
;         *(f32x4*)(out + O_SWKV + so) = S;
	v_lshlrev_b32_e32 v32, 16, v136
	s_nop 1
	v_mov_b32_dpp v24, v32 quad_perm:[0,0,0,0] row_mask:0xf bank_mask:0xf
	v_mov_b32_dpp v26, v32 quad_perm:[1,1,1,1] row_mask:0xf bank_mask:0xf
	v_mov_b32_dpp v28, v32 quad_perm:[2,2,2,2] row_mask:0xf bank_mask:0xf
	v_mov_b32_dpp v30, v32 quad_perm:[3,3,3,3] row_mask:0xf bank_mask:0xf
	v_pk_mul_f32 v[36:37], v[124:125], v[164:165]
	v_pk_mul_f32 v[38:39], v[24:25], v[160:161] op_sel_hi:[0,1]
	v_pk_fma_f32 v[36:37], v[126:127], v[166:167], v[36:37]
	v_pk_mul_f32 v[40:41], v[24:25], v[162:163] op_sel_hi:[0,1]
	v_add_f32_e32 v36, v36, v37
	s_nop 1
	v_add_f32_dpp v36, v36, v36 quad_perm:[1,0,3,2] row_mask:0xf bank_mask:0xf bound_ctrl:1
	s_nop 1
	v_add_f32_dpp v36, v36, v36 quad_perm:[2,3,0,1] row_mask:0xf bank_mask:0xf bound_ctrl:1
	s_nop 1
	v_add_f32_dpp v36, v36, v36 row_half_mirror row_mask:0xf bank_mask:0xf bound_ctrl:1
	s_nop 1
	v_add_f32_dpp v36, v36, v36 row_mirror row_mask:0xf bank_mask:0xf bound_ctrl:1
	v_pk_fma_f32 v[38:39], v[36:37], v[168:169], v[38:39] op_sel_hi:[0,1,1] neg_lo:[1,0,0] neg_hi:[1,0,0]
	v_pk_fma_f32 v[40:41], v[36:37], v[170:171], v[40:41] op_sel_hi:[0,1,1] neg_lo:[1,0,0] neg_hi:[1,0,0]
	v_pk_fma_f32 v[124:125], v[124:125], v[156:157], v[38:39]
	v_pk_fma_f32 v[126:127], v[126:127], v[158:159], v[40:41]
	v_pk_mul_f32 v[36:37], v[124:125], v[192:193]
	v_pk_mul_f32 v[42:43], v[124:125], v[152:153]
	v_pk_mul_f32 v[38:39], v[26:27], v[188:189] op_sel_hi:[0,1]
	v_pk_fma_f32 v[42:43], v[126:127], v[154:155], v[42:43]
	v_pk_fma_f32 v[36:37], v[126:127], v[194:195], v[36:37]
	v_add_f32_e32 v44, v42, v43
	v_pk_mul_f32 v[40:41], v[26:27], v[190:191] op_sel_hi:[0,1]
	v_add_f32_e32 v36, v36, v37
	v_add_f32_dpp v44, v44, v44 quad_perm:[1,0,3,2] row_mask:0xf bank_mask:0xf bound_ctrl:1
	s_nop 0
	v_add_f32_dpp v36, v36, v36 quad_perm:[1,0,3,2] row_mask:0xf bank_mask:0xf bound_ctrl:1
	v_add_f32_dpp v44, v44, v44 quad_perm:[2,3,0,1] row_mask:0xf bank_mask:0xf bound_ctrl:1
	s_nop 0
	v_add_f32_dpp v36, v36, v36 quad_perm:[2,3,0,1] row_mask:0xf bank_mask:0xf bound_ctrl:1
	v_add_f32_dpp v44, v44, v44 row_half_mirror row_mask:0xf bank_mask:0xf bound_ctrl:1
	s_nop 0
	v_add_f32_dpp v36, v36, v36 row_half_mirror row_mask:0xf bank_mask:0xf bound_ctrl:1
	v_add_f32_dpp v44, v44, v44 row_mirror row_mask:0xf bank_mask:0xf bound_ctrl:1
	s_nop 0
	v_add_f32_dpp v36, v36, v36 row_mirror row_mask:0xf bank_mask:0xf bound_ctrl:1
	v_pk_fma_f32 v[38:39], v[36:37], v[196:197], v[38:39] op_sel_hi:[0,1,1] neg_lo:[1,0,0] neg_hi:[1,0,0]
	v_pk_fma_f32 v[40:41], v[36:37], v[198:199], v[40:41] op_sel_hi:[0,1,1] neg_lo:[1,0,0] neg_hi:[1,0,0]
	v_pk_fma_f32 v[124:125], v[124:125], v[180:181], v[38:39]
	v_pk_fma_f32 v[126:127], v[126:127], v[182:183], v[40:41]
	v_pk_mul_f32 v[36:37], v[124:125], v[212:213]
	v_pk_mul_f32 v[42:43], v[124:125], v[176:177]
	v_pk_mul_f32 v[38:39], v[28:29], v[208:209] op_sel_hi:[0,1]
	v_pk_fma_f32 v[42:43], v[126:127], v[178:179], v[42:43]
	v_pk_fma_f32 v[36:37], v[126:127], v[214:215], v[36:37]
	v_add_f32_e32 v45, v42, v43
	v_pk_mul_f32 v[40:41], v[28:29], v[210:211] op_sel_hi:[0,1]
	v_add_f32_e32 v36, v36, v37
	v_add_f32_dpp v45, v45, v45 quad_perm:[1,0,3,2] row_mask:0xf bank_mask:0xf bound_ctrl:1
	s_nop 0
	v_add_f32_dpp v36, v36, v36 quad_perm:[1,0,3,2] row_mask:0xf bank_mask:0xf bound_ctrl:1
	v_add_f32_dpp v45, v45, v45 quad_perm:[2,3,0,1] row_mask:0xf bank_mask:0xf bound_ctrl:1
	s_nop 0
	v_add_f32_dpp v36, v36, v36 quad_perm:[2,3,0,1] row_mask:0xf bank_mask:0xf bound_ctrl:1
	v_add_f32_dpp v45, v45, v45 row_half_mirror row_mask:0xf bank_mask:0xf bound_ctrl:1
	s_nop 0
	v_add_f32_dpp v36, v36, v36 row_half_mirror row_mask:0xf bank_mask:0xf bound_ctrl:1
	v_add_f32_dpp v45, v45, v45 row_mirror row_mask:0xf bank_mask:0xf bound_ctrl:1
	s_nop 0
	v_add_f32_dpp v36, v36, v36 row_mirror row_mask:0xf bank_mask:0xf bound_ctrl:1
	v_pk_fma_f32 v[38:39], v[36:37], v[216:217], v[38:39] op_sel_hi:[0,1,1] neg_lo:[1,0,0] neg_hi:[1,0,0]
	v_pk_fma_f32 v[40:41], v[36:37], v[218:219], v[40:41] op_sel_hi:[0,1,1] neg_lo:[1,0,0] neg_hi:[1,0,0]
	v_pk_fma_f32 v[124:125], v[124:125], v[204:205], v[38:39]
	v_pk_fma_f32 v[126:127], v[126:127], v[206:207], v[40:41]
	v_pk_mul_f32 v[36:37], v[124:125], v[232:233]
	v_pk_mul_f32 v[42:43], v[124:125], v[200:201]
	v_pk_mul_f32 v[38:39], v[30:31], v[228:229] op_sel_hi:[0,1]
	v_pk_fma_f32 v[42:43], v[126:127], v[202:203], v[42:43]
	v_pk_fma_f32 v[36:37], v[126:127], v[234:235], v[36:37]
	v_add_f32_e32 v46, v42, v43
	v_pk_mul_f32 v[40:41], v[30:31], v[230:231] op_sel_hi:[0,1]
	v_add_f32_e32 v36, v36, v37
	v_add_f32_dpp v46, v46, v46 quad_perm:[1,0,3,2] row_mask:0xf bank_mask:0xf bound_ctrl:1
	s_nop 0
	v_add_f32_dpp v36, v36, v36 quad_perm:[1,0,3,2] row_mask:0xf bank_mask:0xf bound_ctrl:1
	v_add_f32_dpp v46, v46, v46 quad_perm:[2,3,0,1] row_mask:0xf bank_mask:0xf bound_ctrl:1
	s_nop 0
	v_add_f32_dpp v36, v36, v36 quad_perm:[2,3,0,1] row_mask:0xf bank_mask:0xf bound_ctrl:1
	v_add_f32_dpp v46, v46, v46 row_half_mirror row_mask:0xf bank_mask:0xf bound_ctrl:1
	s_nop 0
	v_add_f32_dpp v36, v36, v36 row_half_mirror row_mask:0xf bank_mask:0xf bound_ctrl:1
	v_add_f32_dpp v46, v46, v46 row_mirror row_mask:0xf bank_mask:0xf bound_ctrl:1
	s_nop 0
	v_add_f32_dpp v36, v36, v36 row_mirror row_mask:0xf bank_mask:0xf bound_ctrl:1
	v_pk_fma_f32 v[38:39], v[36:37], v[242:243], v[38:39] op_sel_hi:[0,1,1] neg_lo:[1,0,0] neg_hi:[1,0,0]
	v_pk_fma_f32 v[40:41], v[36:37], v[244:245], v[40:41] op_sel_hi:[0,1,1] neg_lo:[1,0,0] neg_hi:[1,0,0]
	v_pk_fma_f32 v[124:125], v[124:125], v[224:225], v[38:39]
	v_pk_fma_f32 v[126:127], v[126:127], v[226:227], v[40:41]
	global_store_dwordx4 v[6:7], v[124:127], off offset:2048
	v_pk_mul_f32 v[42:43], v[124:125], v[220:221]
	v_pk_fma_f32 v[42:43], v[126:127], v[222:223], v[42:43]
	v_add_f32_e32 v47, v42, v43
	s_nop 1
	v_add_f32_dpp v47, v47, v47 quad_perm:[1,0,3,2] row_mask:0xf bank_mask:0xf bound_ctrl:1
	s_nop 1
	v_add_f32_dpp v47, v47, v47 quad_perm:[2,3,0,1] row_mask:0xf bank_mask:0xf bound_ctrl:1
	s_nop 1
	v_add_f32_dpp v47, v47, v47 row_half_mirror row_mask:0xf bank_mask:0xf bound_ctrl:1
	s_nop 1
	v_add_f32_dpp v47, v47, v47 row_mirror row_mask:0xf bank_mask:0xf bound_ctrl:1
	v_cndmask_b32_e64 v48, v44, v45, s[8:9]
	v_cndmask_b32_e64 v48, v48, v46, s[12:13]
	s_nop 1
	v_cndmask_b32_e64 v48, v48, v47, s[14:15]
	s_and_saveexec_b64 s[6:7], s[18:19]
	ds_write_b32 v17, v48 offset:96
	s_mov_b64 exec, s[6:7]
	s_waitcnt vmcnt(7)
; __device__ __forceinline__ float bf2f(bf16_t h) { return __uint_as_float((unsigned)h << 16); }
; __device__ __forceinline__ bf16_t f2bf(float f) { return (bf16_t)(cvt_pk_bf16(f, 0.f) & 0xffffu); }
; __device__ __forceinline__ f32x4 unpack4(const u32x2 w) { return (f32x4){__uint_as_float(w[0] << 16), __uint_as_float(w[0] & 0xffff0000u), __uint_as_float(w[1] << 16), __uint_as_float(w[1] & 0xffff0000u)}; }
; __device__ __forceinline__ void scan_wkv_sample(PP P, int l, const Ids I) {
;     ...
;     for (int q = gw; q < 128 * 8 * 16; q += nw) {
;         const int pair = q >> 4, rgp = q & 15, sb = pair >> 3, h = pair & 7, vrow = rgp * 4 + rowl;
;         const unsigned so = ((unsigned)((l * 128 + sb) * 8 + h) * 64u + vrow) * 64u + kseg * 4;
;         f32x4 S = *(const f32x4*)(sin_ + so);
;         f32x4 r_[4], w_[4], k_[4], a_[4], b_[4]; float v_[4];
; #pragma unroll
;         for (int s = 0; s < 4; ++s) { const unsigned row = (unsigned)MTP + sb * 4 + s, o = row * 512u + h * 64 + kseg * 4;
;             r_[s] = unpack4(*(const u32x2*)(arr + A_R * AS + o)); w_[s] = unpack4(*(const u32x2*)(arr + A_EW * AS + o)); k_[s] = unpack4(*(const u32x2*)(arr + A_KF * AS + o));
;             a_[s] = unpack4(*(const u32x2*)(arr + A_KK * AS + o)); b_[s] = unpack4(*(const u32x2*)(arr + A_BB * AS + o)); v_[s] = bf2f(arr[A_V * AS + row * 512u + h * 64 + vrow]); }
; #pragma unroll
;         for (int s = 0; s < 4; ++s) { const unsigned row = (unsigned)MTP + sb * 4 + s;
;             const float p = (S[0] * a_[s][0] + S[1] * a_[s][1]) + (S[2] * a_[s][2] + S[3] * a_[s][3]); const float sa = -row16_allsum(p);
; #pragma unroll
;             for (int j = 0; j < 4; ++j) S[j] = fmaf(S[j], __expf(-w_[s][j]), fmaf(sa, b_[s][j], v_[s] * k_[s][j]));
;             const float y = row16_allsum((S[0] * r_[s][0] + S[1] * r_[s][1]) + (S[2] * r_[s][2] + S[3] * r_[s][3]));
;             if (kseg == 0) ymix[row * 1024u + 512u + h * 64 + vrow] = f2bf(y); }
;         *(f32x4*)(out + O_SWKV + so) = S;
;     }
	v_lshlrev_b32_e32 v32, 16, v137
	s_nop 1
	v_mov_b32_dpp v24, v32 quad_perm:[0,0,0,0] row_mask:0xf bank_mask:0xf
	v_mov_b32_dpp v26, v32 quad_perm:[1,1,1,1] row_mask:0xf bank_mask:0xf
	v_mov_b32_dpp v28, v32 quad_perm:[2,2,2,2] row_mask:0xf bank_mask:0xf
	v_mov_b32_dpp v30, v32 quad_perm:[3,3,3,3] row_mask:0xf bank_mask:0xf
	v_pk_mul_f32 v[36:37], v[128:129], v[164:165]
	v_pk_mul_f32 v[38:39], v[24:25], v[160:161] op_sel_hi:[0,1]
	v_pk_fma_f32 v[36:37], v[130:131], v[166:167], v[36:37]
	v_pk_mul_f32 v[40:41], v[24:25], v[162:163] op_sel_hi:[0,1]
	v_add_f32_e32 v36, v36, v37
	s_nop 1
	v_add_f32_dpp v36, v36, v36 quad_perm:[1,0,3,2] row_mask:0xf bank_mask:0xf bound_ctrl:1
	s_nop 1
	v_add_f32_dpp v36, v36, v36 quad_perm:[2,3,0,1] row_mask:0xf bank_mask:0xf bound_ctrl:1
	s_nop 1
	v_add_f32_dpp v36, v36, v36 row_half_mirror row_mask:0xf bank_mask:0xf bound_ctrl:1
	s_nop 1
	v_add_f32_dpp v36, v36, v36 row_mirror row_mask:0xf bank_mask:0xf bound_ctrl:1
	v_pk_fma_f32 v[38:39], v[36:37], v[168:169], v[38:39] op_sel_hi:[0,1,1] neg_lo:[1,0,0] neg_hi:[1,0,0]
	v_pk_fma_f32 v[40:41], v[36:37], v[170:171], v[40:41] op_sel_hi:[0,1,1] neg_lo:[1,0,0] neg_hi:[1,0,0]
	v_pk_fma_f32 v[128:129], v[128:129], v[156:157], v[38:39]
	v_pk_fma_f32 v[130:131], v[130:131], v[158:159], v[40:41]
	v_pk_mul_f32 v[36:37], v[128:129], v[192:193]
	v_pk_mul_f32 v[42:43], v[128:129], v[152:153]
	v_pk_mul_f32 v[38:39], v[26:27], v[188:189] op_sel_hi:[0,1]
	v_pk_fma_f32 v[42:43], v[130:131], v[154:155], v[42:43]
	v_pk_fma_f32 v[36:37], v[130:131], v[194:195], v[36:37]
	v_add_f32_e32 v44, v42, v43
	v_pk_mul_f32 v[40:41], v[26:27], v[190:191] op_sel_hi:[0,1]
	v_add_f32_e32 v36, v36, v37
	v_add_f32_dpp v44, v44, v44 quad_perm:[1,0,3,2] row_mask:0xf bank_mask:0xf bound_ctrl:1
	s_nop 0
	v_add_f32_dpp v36, v36, v36 quad_perm:[1,0,3,2] row_mask:0xf bank_mask:0xf bound_ctrl:1
	v_add_f32_dpp v44, v44, v44 quad_perm:[2,3,0,1] row_mask:0xf bank_mask:0xf bound_ctrl:1
	s_nop 0
	v_add_f32_dpp v36, v36, v36 quad_perm:[2,3,0,1] row_mask:0xf bank_mask:0xf bound_ctrl:1
	v_add_f32_dpp v44, v44, v44 row_half_mirror row_mask:0xf bank_mask:0xf bound_ctrl:1
	s_nop 0
	v_add_f32_dpp v36, v36, v36 row_half_mirror row_mask:0xf bank_mask:0xf bound_ctrl:1
	v_add_f32_dpp v44, v44, v44 row_mirror row_mask:0xf bank_mask:0xf bound_ctrl:1
	s_nop 0
	v_add_f32_dpp v36, v36, v36 row_mirror row_mask:0xf bank_mask:0xf bound_ctrl:1
	v_pk_fma_f32 v[38:39], v[36:37], v[196:197], v[38:39] op_sel_hi:[0,1,1] neg_lo:[1,0,0] neg_hi:[1,0,0]
	v_pk_fma_f32 v[40:41], v[36:37], v[198:199], v[40:41] op_sel_hi:[0,1,1] neg_lo:[1,0,0] neg_hi:[1,0,0]
	v_pk_fma_f32 v[128:129], v[128:129], v[180:181], v[38:39]
	v_pk_fma_f32 v[130:131], v[130:131], v[182:183], v[40:41]
	v_pk_mul_f32 v[36:37], v[128:129], v[212:213]
	v_pk_mul_f32 v[42:43], v[128:129], v[176:177]
	v_pk_mul_f32 v[38:39], v[28:29], v[208:209] op_sel_hi:[0,1]
	v_pk_fma_f32 v[42:43], v[130:131], v[178:179], v[42:43]
	v_pk_fma_f32 v[36:37], v[130:131], v[214:215], v[36:37]
	v_add_f32_e32 v45, v42, v43
	v_pk_mul_f32 v[40:41], v[28:29], v[210:211] op_sel_hi:[0,1]
	v_add_f32_e32 v36, v36, v37
	v_add_f32_dpp v45, v45, v45 quad_perm:[1,0,3,2] row_mask:0xf bank_mask:0xf bound_ctrl:1
	s_nop 0
	v_add_f32_dpp v36, v36, v36 quad_perm:[1,0,3,2] row_mask:0xf bank_mask:0xf bound_ctrl:1
	v_add_f32_dpp v45, v45, v45 quad_perm:[2,3,0,1] row_mask:0xf bank_mask:0xf bound_ctrl:1
	s_nop 0
	v_add_f32_dpp v36, v36, v36 quad_perm:[2,3,0,1] row_mask:0xf bank_mask:0xf bound_ctrl:1
	v_add_f32_dpp v45, v45, v45 row_half_mirror row_mask:0xf bank_mask:0xf bound_ctrl:1
	s_nop 0
	v_add_f32_dpp v36, v36, v36 row_half_mirror row_mask:0xf bank_mask:0xf bound_ctrl:1
	v_add_f32_dpp v45, v45, v45 row_mirror row_mask:0xf bank_mask:0xf bound_ctrl:1
	s_nop 0
	v_add_f32_dpp v36, v36, v36 row_mirror row_mask:0xf bank_mask:0xf bound_ctrl:1
	v_pk_fma_f32 v[38:39], v[36:37], v[216:217], v[38:39] op_sel_hi:[0,1,1] neg_lo:[1,0,0] neg_hi:[1,0,0]
	v_pk_fma_f32 v[40:41], v[36:37], v[218:219], v[40:41] op_sel_hi:[0,1,1] neg_lo:[1,0,0] neg_hi:[1,0,0]
	v_pk_fma_f32 v[128:129], v[128:129], v[204:205], v[38:39]
	v_pk_fma_f32 v[130:131], v[130:131], v[206:207], v[40:41]
	v_pk_mul_f32 v[36:37], v[128:129], v[232:233]
	v_pk_mul_f32 v[42:43], v[128:129], v[200:201]
	v_pk_mul_f32 v[38:39], v[30:31], v[228:229] op_sel_hi:[0,1]
	v_pk_fma_f32 v[42:43], v[130:131], v[202:203], v[42:43]
	v_pk_fma_f32 v[36:37], v[130:131], v[234:235], v[36:37]
	v_add_f32_e32 v46, v42, v43
	v_pk_mul_f32 v[40:41], v[30:31], v[230:231] op_sel_hi:[0,1]
	v_add_f32_e32 v36, v36, v37
	v_add_f32_dpp v46, v46, v46 quad_perm:[1,0,3,2] row_mask:0xf bank_mask:0xf bound_ctrl:1
	s_nop 0
	v_add_f32_dpp v36, v36, v36 quad_perm:[1,0,3,2] row_mask:0xf bank_mask:0xf bound_ctrl:1
	v_add_f32_dpp v46, v46, v46 quad_perm:[2,3,0,1] row_mask:0xf bank_mask:0xf bound_ctrl:1
	s_nop 0
	v_add_f32_dpp v36, v36, v36 quad_perm:[2,3,0,1] row_mask:0xf bank_mask:0xf bound_ctrl:1
	v_add_f32_dpp v46, v46, v46 row_half_mirror row_mask:0xf bank_mask:0xf bound_ctrl:1
	s_nop 0
	v_add_f32_dpp v36, v36, v36 row_half_mirror row_mask:0xf bank_mask:0xf bound_ctrl:1
	v_add_f32_dpp v46, v46, v46 row_mirror row_mask:0xf bank_mask:0xf bound_ctrl:1
	s_nop 0
	v_add_f32_dpp v36, v36, v36 row_mirror row_mask:0xf bank_mask:0xf bound_ctrl:1
	v_pk_fma_f32 v[38:39], v[36:37], v[242:243], v[38:39] op_sel_hi:[0,1,1] neg_lo:[1,0,0] neg_hi:[1,0,0]
	v_pk_fma_f32 v[40:41], v[36:37], v[244:245], v[40:41] op_sel_hi:[0,1,1] neg_lo:[1,0,0] neg_hi:[1,0,0]
	v_pk_fma_f32 v[128:129], v[128:129], v[224:225], v[38:39]
	v_pk_fma_f32 v[130:131], v[130:131], v[226:227], v[40:41]
	global_store_dwordx4 v[6:7], v[128:131], off offset:3072
	v_pk_mul_f32 v[42:43], v[128:129], v[220:221]
	v_pk_fma_f32 v[42:43], v[130:131], v[222:223], v[42:43]
	v_add_f32_e32 v47, v42, v43
	s_nop 1
	v_add_f32_dpp v47, v47, v47 quad_perm:[1,0,3,2] row_mask:0xf bank_mask:0xf bound_ctrl:1
	s_nop 1
	v_add_f32_dpp v47, v47, v47 quad_perm:[2,3,0,1] row_mask:0xf bank_mask:0xf bound_ctrl:1
	s_nop 1
	v_add_f32_dpp v47, v47, v47 row_half_mirror row_mask:0xf bank_mask:0xf bound_ctrl:1
	s_nop 1
	v_add_f32_dpp v47, v47, v47 row_mirror row_mask:0xf bank_mask:0xf bound_ctrl:1
	v_cndmask_b32_e64 v48, v44, v45, s[8:9]
	v_cndmask_b32_e64 v48, v48, v46, s[12:13]
	s_nop 1
	v_cndmask_b32_e64 v48, v48, v47, s[14:15]
	s_and_saveexec_b64 s[6:7], s[18:19]
	ds_write_b32 v17, v48 offset:112
	s_mov_b64 exec, s[6:7]
	s_waitcnt lgkmcnt(0)
	s_and_saveexec_b64 s[6:7], s[0:1]
	ds_read_b128 v[20:23], v19
	ds_read_b128 v[24:27], v19 offset:16
	s_waitcnt lgkmcnt(0)
	v_cvt_pk_bf16_f32 v20, v20, v21
	v_cvt_pk_bf16_f32 v21, v22, v23
	v_cvt_pk_bf16_f32 v22, v24, v25
	v_cvt_pk_bf16_f32 v23, v26, v27
	global_store_dwordx4 v[10:11], v[20:23], off
	s_mov_b64 exec, s[6:7]
	s_branch .LBB0_754
; __device__ __forceinline__ int make_tid(int wv) { int lane_v; asm volatile("v_mbcnt_lo_u32_b32 %0, -1, 0\n\tv_mbcnt_hi_u32_b32 %0, -1, %0" : "=v"(lane_v)); return wv * 64 + lane_v; }
; __device__ __forceinline__ float bf2f(bf16_t h) { return __uint_as_float((unsigned)h << 16); }
; __device__ __forceinline__ bf16_t f2bf(float f) { return (bf16_t)(cvt_pk_bf16(f, 0.f) & 0xffffu); }
; __device__ __forceinline__ void scan_wkv_sample(PP P, int l, const Ids I) {
;     const int tid = make_tid(I.wv), wave = __builtin_amdgcn_readfirstlane(tid >> 6), lane = tid & 63, rowl = lane >> 4, kseg = lane & 15; unsigned char* ws = P->ws;
;     const bf16_t* arr = (const bf16_t*)(ws + WS_R2); const unsigned AS = (unsigned)MT * 512u; bf16_t* ymix = (bf16_t*)(ws + WS_HB);
;     const float* sin_ = P->in[I_SWKV]; float* out = P->out;
;     const int gw = BID * 8 + wave, nw = NB * 8;
;     for (int q = gw; q < 128 * 8 * 16; q += nw) {
;         const int pair = q >> 4, rgp = q & 15, sb = pair >> 3, h = pair & 7, vrow = rgp * 4 + rowl;
;         const unsigned so = ((unsigned)((l * 128 + sb) * 8 + h) * 64u + vrow) * 64u + kseg * 4;
;         f32x4 S = *(const f32x4*)(sin_ + so);
;         f32x4 r_[4], w_[4], k_[4], a_[4], b_[4]; float v_[4];
; #pragma unroll
;         for (int s = 0; s < 4; ++s) { const unsigned row = (unsigned)MTP + sb * 4 + s, o = row * 512u + h * 64 + kseg * 4;
;             r_[s] = unpack4(*(const u32x2*)(arr + A_R * AS + o)); w_[s] = unpack4(*(const u32x2*)(arr + A_EW * AS + o)); k_[s] = unpack4(*(const u32x2*)(arr + A_KF * AS + o));
;             a_[s] = unpack4(*(const u32x2*)(arr + A_KK * AS + o)); b_[s] = unpack4(*(const u32x2*)(arr + A_BB * AS + o)); v_[s] = bf2f(arr[A_V * AS + row * 512u + h * 64 + vrow]); }
; #pragma unroll
;         for (int s = 0; s < 4; ++s) { const unsigned row = (unsigned)MTP + sb * 4 + s;
;             const float p = (S[0] * a_[s][0] + S[1] * a_[s][1]) + (S[2] * a_[s][2] + S[3] * a_[s][3]); const float sa = -row16_allsum(p);
; #pragma unroll
;             for (int j = 0; j < 4; ++j) S[j] = fmaf(S[j], __expf(-w_[s][j]), fmaf(sa, b_[s][j], v_[s] * k_[s][j]));
;             const float y = row16_allsum((S[0] * r_[s][0] + S[1] * r_[s][1]) + (S[2] * r_[s][2] + S[3] * r_[s][3]));
;             if (kseg == 0) ymix[row * 1024u + 512u + h * 64 + vrow] = f2bf(y); }
;         *(f32x4*)(out + O_SWKV + so) = S;
;     }
; }
	s_nop 0
	s_nop 0
	s_nop 0
	s_nop 0
	s_nop 0
	s_nop 0
	s_nop 0
	s_nop 0
	s_nop 0
	s_nop 0
	s_nop 0
	s_nop 0
	s_nop 0
	s_nop 0
	s_nop 0
	s_nop 0
	s_nop 0
	s_nop 0
	s_nop 0
	s_nop 0
	s_nop 0
	s_nop 0
	s_nop 0
	s_nop 0
	s_nop 0
	s_nop 0
	s_nop 0
	s_nop 0
	s_nop 0
	s_nop 0
	s_nop 0
	s_nop 0
	s_nop 0
	s_nop 0
	s_nop 0
	s_nop 0
	s_nop 0
	s_nop 0
	s_nop 0
	s_nop 0
	s_nop 0
	s_nop 0
	s_nop 0
	s_nop 0
	s_nop 0
	s_nop 0
	s_nop 0
	s_nop 0
	s_nop 0
	s_nop 0
	s_nop 0
	s_nop 0
	s_nop 0
	s_nop 0
	s_nop 0
	s_nop 0
